# write-through (sc0 sc1) stores also in P2, P3, P4, P6, P7 on top of the stacked variant
# baseline (speedup 1.0000x reference)
.LBB0_338:
	s_or_b64 exec, exec, s[30:31]
	s_waitcnt lgkmcnt(0)
	s_barrier
	ds_read_b128 v[0:3], v161
	ds_read_b128 v[4:7], v162
	s_lshl_b32 s10, s40, 4
	s_waitcnt lgkmcnt(0)
	v_mfma_f32_32x32x16_bf16 v[48:63], v[0:3], v[4:7], 0
	ds_read_b128 v[4:7], v163
	ds_read_b128 v[8:11], v164
	s_or_b32 s10, s10, s41
	v_add_u32_e32 v136, s10, v85
	v_ashrrev_i32_e32 v137, 31, v136
	v_lshlrev_b64 v[136:137], 15, v[136:137]
	v_lshl_add_u64 v[136:137], s[16:17], 0, v[136:137]
	v_mov_b32_e32 v85, v83
	s_waitcnt lgkmcnt(1)
	v_mfma_f32_32x32x16_bf16 v[32:47], v[0:3], v[4:7], 0
	ds_read_b128 v[4:7], v165
	ds_read_b128 v[64:67], v166
	ds_read_b128 v[68:71], v167
	ds_read_b128 v[72:75], v168
	v_mov_b32_e32 v87, v83
	v_mov_b32_e32 v89, v83
	v_mov_b32_e32 v91, v83
	v_mov_b32_e32 v93, v83
	v_mov_b32_e32 v95, v83
	s_waitcnt lgkmcnt(4)
	v_mfma_f32_32x32x16_bf16 v[16:31], v[0:3], v[8:11], 0
	v_mov_b32_e32 v97, v83
	v_mov_b32_e32 v99, v83
	v_mov_b32_e32 v101, v83
	v_mov_b32_e32 v103, v83
	v_mov_b32_e32 v105, v83
	v_mov_b32_e32 v107, v83
	v_mov_b32_e32 v109, v83
	s_waitcnt lgkmcnt(3)
	v_mfma_f32_32x32x16_bf16 v[0:15], v[0:3], v[4:7], 0
	v_mov_b32_e32 v111, v83
	v_mov_b32_e32 v113, v83
	v_mov_b32_e32 v115, v83
	s_add_i32 s39, s39, s88
	s_cmpk_lt_i32 s39, 0x100
	s_waitcnt lgkmcnt(1)
	v_mfma_f32_32x32x16_bf16 v[48:63], v[64:67], v[68:71], v[48:63]
	s_waitcnt lgkmcnt(0)
	v_mfma_f32_32x32x16_bf16 v[32:47], v[64:67], v[72:75], v[32:47]
	ds_read_b128 v[68:71], v169
	ds_read_b128 v[72:75], v170
	s_waitcnt lgkmcnt(1)
	v_mfma_f32_32x32x16_bf16 v[16:31], v[64:67], v[68:71], v[16:31]
	s_waitcnt lgkmcnt(0)
	v_mfma_f32_32x32x16_bf16 v[0:15], v[64:67], v[72:75], v[0:15]
	ds_read_b128 v[64:67], v171
	ds_read_b128 v[68:71], v172
	s_waitcnt lgkmcnt(0)
	v_mfma_f32_32x32x16_bf16 v[48:63], v[64:67], v[68:71], v[48:63]
	ds_read_b128 v[68:71], v173
	ds_read_b128 v[72:75], v174
	s_waitcnt lgkmcnt(1)
	v_mfma_f32_32x32x16_bf16 v[32:47], v[64:67], v[68:71], v[32:47]
	s_waitcnt lgkmcnt(0)
	v_mfma_f32_32x32x16_bf16 v[16:31], v[64:67], v[72:75], v[16:31]
	ds_read_b128 v[68:71], v175
	ds_read_b128 v[72:75], v176
	s_waitcnt lgkmcnt(1)
	v_mfma_f32_32x32x16_bf16 v[0:15], v[64:67], v[68:71], v[0:15]
	ds_read_b128 v[64:67], v177
	ds_read_b128 v[68:71], v178
	s_waitcnt lgkmcnt(1)
	v_mfma_f32_32x32x16_bf16 v[48:63], v[72:75], v[64:67], v[48:63]
	s_waitcnt lgkmcnt(0)
	v_mfma_f32_32x32x16_bf16 v[32:47], v[72:75], v[68:71], v[32:47]
	ds_read_b128 v[64:67], v179
	ds_read_b128 v[68:71], v180
	s_waitcnt lgkmcnt(1)
	v_mfma_f32_32x32x16_bf16 v[16:31], v[72:75], v[64:67], v[16:31]
	s_waitcnt lgkmcnt(0)
	v_mfma_f32_32x32x16_bf16 v[0:15], v[72:75], v[68:71], v[0:15]
	ds_read_b128 v[64:67], v181
	ds_read_b128 v[68:71], v182
	s_waitcnt lgkmcnt(0)
	v_mfma_f32_32x32x16_bf16 v[48:63], v[64:67], v[68:71], v[48:63]
	ds_read_b128 v[68:71], v186
	ds_read_b128 v[72:75], v187
	ds_read_b128 v[76:79], v185
	ds_read_b128 v[116:119], v188
	ds_read_b128 v[120:123], v191
	s_waitcnt lgkmcnt(3)
	v_mfma_f32_32x32x16_bf16 v[48:63], v[68:71], v[72:75], v[48:63]
	ds_read_b128 v[72:75], v183
	ds_read_b128 v[124:127], v184
	ds_read_b128 v[128:131], v192
	ds_read_b128 v[132:135], v189
	ds_read_b128 v[202:205], v190
	ds_read_b128 v[206:209], v195
	ds_read_b128 v[210:213], v196
	s_waitcnt lgkmcnt(6)
	v_mfma_f32_32x32x16_bf16 v[32:47], v[64:67], v[72:75], v[32:47]
	v_lshl_add_u64 v[72:73], v[136:137], 0, v[92:93]
	v_lshl_add_u64 v[74:75], v[136:137], 0, v[104:105]
	s_waitcnt lgkmcnt(5)
	v_mfma_f32_32x32x16_bf16 v[16:31], v[64:67], v[124:127], v[16:31]
	v_mfma_f32_32x32x16_bf16 v[0:15], v[64:67], v[76:79], v[0:15]
	v_lshl_add_u64 v[64:65], v[136:137], 0, v[96:97]
	v_lshl_add_u64 v[66:67], v[136:137], 0, v[100:101]
	v_lshl_add_u64 v[76:77], v[136:137], 0, v[108:109]
	v_lshl_add_u64 v[78:79], v[136:137], 0, v[114:115]
	v_mfma_f32_32x32x16_bf16 v[32:47], v[68:71], v[116:119], v[32:47]
	s_waitcnt lgkmcnt(4)
	v_mfma_f32_32x32x16_bf16 v[48:63], v[120:123], v[128:131], v[48:63]
	ds_read_b128 v[128:131], v193
	ds_read_b128 v[214:217], v194
	ds_read_b128 v[218:221], v197
	ds_read_b128 v[222:225], v198
	ds_read_b128 v[226:229], v199
	ds_read_b128 v[230:233], v200
	s_waitcnt lgkmcnt(9)
	v_mfma_f32_32x32x16_bf16 v[16:31], v[68:71], v[132:135], v[16:31]
	s_waitcnt lgkmcnt(8)
	v_mfma_f32_32x32x16_bf16 v[0:15], v[68:71], v[202:205], v[0:15]
	s_waitcnt lgkmcnt(5)
	v_mfma_f32_32x32x16_bf16 v[32:47], v[120:123], v[128:131], v[32:47]
	s_waitcnt lgkmcnt(3)
	v_mfma_f32_32x32x16_bf16 v[48:63], v[210:213], v[218:221], v[48:63]
	v_lshl_add_u64 v[218:219], v[136:137], 0, v[84:85]
	v_mfma_f32_32x32x16_bf16 v[16:31], v[120:123], v[214:217], v[16:31]
	s_nop 9
	global_store_dword v[218:219], v48, off sc0 sc1
	global_store_dword v[218:219], v49, off offset:512 sc0 sc1
	global_store_dword v[218:219], v50, off offset:1024 sc0 sc1
	global_store_dword v[218:219], v51, off offset:1536 sc0 sc1
	v_lshl_add_u64 v[48:49], v[136:137], 0, v[86:87]
	v_lshl_add_u64 v[50:51], v[136:137], 0, v[88:89]
	global_store_dword v[48:49], v52, off sc0 sc1
	global_store_dword v[50:51], v53, off sc0 sc1
	v_lshl_add_u64 v[52:53], v[136:137], 0, v[90:91]
	v_mfma_f32_32x32x16_bf16 v[0:15], v[120:123], v[206:209], v[0:15]
	global_store_dword v[52:53], v54, off sc0 sc1
	global_store_dword v[72:73], v55, off sc0 sc1
	v_lshl_add_u64 v[54:55], v[136:137], 0, v[94:95]
	global_store_dword v[54:55], v56, off sc0 sc1
	global_store_dword v[64:65], v57, off sc0 sc1
	v_lshl_add_u64 v[56:57], v[136:137], 0, v[98:99]
	global_store_dword v[56:57], v58, off sc0 sc1
	s_waitcnt lgkmcnt(2)
	v_mfma_f32_32x32x16_bf16 v[32:47], v[210:213], v[222:225], v[32:47]
	global_store_dword v[66:67], v59, off sc0 sc1
	v_lshl_add_u64 v[58:59], v[136:137], 0, v[102:103]
	global_store_dword v[58:59], v60, off sc0 sc1
	global_store_dword v[74:75], v61, off sc0 sc1
	v_lshl_add_u64 v[60:61], v[136:137], 0, v[106:107]
	global_store_dword v[60:61], v62, off sc0 sc1
	global_store_dword v[76:77], v63, off sc0 sc1
	s_nop 4
	global_store_dword v[218:219], v32, off offset:128 sc0 sc1
	s_waitcnt lgkmcnt(1)
	v_mfma_f32_32x32x16_bf16 v[16:31], v[210:213], v[226:229], v[16:31]
	v_lshl_add_u64 v[62:63], v[136:137], 0, v[110:111]
	global_store_dword v[62:63], v33, off offset:128 sc0 sc1
	v_lshl_add_u64 v[32:33], v[136:137], 0, v[112:113]
	global_store_dword v[32:33], v34, off offset:128 sc0 sc1
	global_store_dword v[78:79], v35, off offset:128 sc0 sc1
	global_store_dword v[48:49], v36, off offset:128 sc0 sc1
	global_store_dword v[50:51], v37, off offset:128 sc0 sc1
	global_store_dword v[52:53], v38, off offset:128 sc0 sc1
	global_store_dword v[72:73], v39, off offset:128 sc0 sc1
	global_store_dword v[54:55], v40, off offset:128 sc0 sc1
	global_store_dword v[64:65], v41, off offset:128 sc0 sc1
	global_store_dword v[56:57], v42, off offset:128 sc0 sc1
	global_store_dword v[66:67], v43, off offset:128 sc0 sc1
	global_store_dword v[58:59], v44, off offset:128 sc0 sc1
	global_store_dword v[74:75], v45, off offset:128 sc0 sc1
	global_store_dword v[60:61], v46, off offset:128 sc0 sc1
	global_store_dword v[76:77], v47, off offset:128 sc0 sc1
	global_store_dword v[218:219], v16, off offset:256 sc0 sc1
	global_store_dword v[62:63], v17, off offset:256 sc0 sc1
	s_waitcnt lgkmcnt(0)
	v_mfma_f32_32x32x16_bf16 v[0:15], v[210:213], v[230:233], v[0:15]
	global_store_dword v[32:33], v18, off offset:256 sc0 sc1
	global_store_dword v[78:79], v19, off offset:256 sc0 sc1
	global_store_dword v[48:49], v20, off offset:256 sc0 sc1
	global_store_dword v[50:51], v21, off offset:256 sc0 sc1
	global_store_dword v[52:53], v22, off offset:256 sc0 sc1
	global_store_dword v[72:73], v23, off offset:256 sc0 sc1
	global_store_dword v[54:55], v24, off offset:256 sc0 sc1
	global_store_dword v[64:65], v25, off offset:256 sc0 sc1
	global_store_dword v[56:57], v26, off offset:256 sc0 sc1
	global_store_dword v[66:67], v27, off offset:256 sc0 sc1
	global_store_dword v[58:59], v28, off offset:256 sc0 sc1
	global_store_dword v[74:75], v29, off offset:256 sc0 sc1
	global_store_dword v[60:61], v30, off offset:256 sc0 sc1
	global_store_dword v[76:77], v31, off offset:256 sc0 sc1
	global_store_dword v[218:219], v0, off offset:384 sc0 sc1
	global_store_dword v[62:63], v1, off offset:384 sc0 sc1
	global_store_dword v[32:33], v2, off offset:384 sc0 sc1
	global_store_dword v[78:79], v3, off offset:384 sc0 sc1
	global_store_dword v[48:49], v4, off offset:384 sc0 sc1
	global_store_dword v[50:51], v5, off offset:384 sc0 sc1
	global_store_dword v[52:53], v6, off offset:384 sc0 sc1
	global_store_dword v[72:73], v7, off offset:384 sc0 sc1
	global_store_dword v[54:55], v8, off offset:384 sc0 sc1
	global_store_dword v[64:65], v9, off offset:384 sc0 sc1
	global_store_dword v[56:57], v10, off offset:384 sc0 sc1
	global_store_dword v[66:67], v11, off offset:384 sc0 sc1
	global_store_dword v[58:59], v12, off offset:384 sc0 sc1
	global_store_dword v[74:75], v13, off offset:384 sc0 sc1
	global_store_dword v[60:61], v14, off offset:384 sc0 sc1
	global_store_dword v[76:77], v15, off offset:384 sc0 sc1
	s_cbranch_scc0 .LBB0_388

.LBB0_345:
	s_or_b64 exec, exec, s[10:11]
	v_add_f32_e32 v0, v0, v1
	s_barrier
	ds_write_b32 v142, v0
	s_waitcnt lgkmcnt(0)
	s_barrier
	ds_read_b32 v0, v140 offset:2556
	ds_read_b32 v1, v143 offset:2048
	ds_read_b32 v2, v139 offset:4096
	v_lshl_or_b32 v85, s35, 8, v80
	s_waitcnt lgkmcnt(1)
	v_sub_f32_e32 v1, v0, v1
	v_mul_f32_e32 v1, 0x3fb8aa3b, v1
	v_exp_f32_e32 v1, v1
	s_waitcnt lgkmcnt(0)
	v_mul_f32_e32 v1, v2, v1
	ds_write_b32 v143, v1 offset:6144
	s_and_saveexec_b64 s[10:11], s[2:3]
	s_cbranch_execz .LBB0_347
	s_lshl_b32 s20, s40, 4
	s_or_b32 s20, s20, s41
	v_add_u32_e32 v2, s20, v85
	v_ashrrev_i32_e32 v3, 31, v2
	v_lshl_add_u64 v[2:3], v[2:3], 2, s[18:19]
	global_store_dword v[2:3], v0, off sc0 sc1

.LBB0_407:
	s_or_b64 exec, exec, s[10:11]
	v_cndmask_b32_e64 v12, 1.0, v53, s[8:9]
	s_waitcnt lgkmcnt(0)
	v_mul_f32_e32 v17, v12, v32
	v_mul_f32_e32 v32, v12, v33
	v_cvt_pk_bf16_f32 v32, v17, v32
	v_mul_f32_e32 v17, v12, v28
	v_mul_f32_e32 v28, v12, v29
	v_cvt_pk_bf16_f32 v33, v17, v28
	v_mul_f32_e32 v17, v12, v34
	v_mul_f32_e32 v28, v12, v35
	v_cvt_pk_bf16_f32 v34, v17, v28
	v_mul_f32_e32 v17, v12, v30
	v_mul_f32_e32 v12, v12, v31
	v_cvt_pk_bf16_f32 v35, v17, v12
	v_mov_b32_e32 v12, s61
	v_mov_b32_e32 v17, s59
	global_store_dwordx4 v[26:27], v[32:35], off sc0 sc1
	v_cndmask_b32_e64 v27, v12, v17, s[6:7]
	v_mov_b32_e32 v12, s60
	v_mov_b32_e32 v17, s58
	v_cndmask_b32_e64 v26, v12, v17, s[6:7]
	v_mov_b32_e32 v17, v13
	v_lshl_add_u64 v[30:31], v[26:27], 0, v[16:17]
	global_load_dwordx4 v[26:29], v[30:31], off
	s_nop 0
	global_load_dwordx4 v[30:33], v[30:31], off offset:16
	v_lshlrev_b32_e32 v12, 2, v57
	global_load_dword v12, v12, s[52:53]
	s_waitcnt vmcnt(6)
	v_lshlrev_b32_e32 v34, 16, v8
	v_and_b32_e32 v35, 0xffff0000, v8
	v_lshlrev_b32_e32 v58, 16, v9
	v_and_b32_e32 v59, 0xffff0000, v9
	v_pk_mul_f32 v[8:9], v[34:35], v[34:35]
	v_lshlrev_b32_e32 v60, 16, v10
	v_and_b32_e32 v61, 0xffff0000, v10
	v_lshlrev_b32_e32 v62, 16, v11
	v_and_b32_e32 v63, 0xffff0000, v11
	v_pk_mul_f32 v[10:11], v[58:59], v[58:59]
	v_add_f32_e32 v8, v8, v9
	v_add_f32_e32 v8, v10, v8
	v_pk_mul_f32 v[64:65], v[60:61], v[60:61]
	v_add_f32_e32 v8, v11, v8
	v_add_f32_e32 v8, v64, v8
	v_pk_mul_f32 v[66:67], v[62:63], v[62:63]
	v_add_f32_e32 v8, v65, v8
	v_add_f32_e32 v8, v66, v8
	v_add_f32_e32 v8, v67, v8
	ds_bpermute_b32 v9, v43, v8
	s_waitcnt lgkmcnt(0)
	v_add_f32_e32 v8, v8, v9
	ds_bpermute_b32 v9, v44, v8
	s_waitcnt lgkmcnt(0)
	v_add_f32_e32 v8, v8, v9
	ds_bpermute_b32 v9, v45, v8
	s_waitcnt lgkmcnt(0)
	v_add_f32_e32 v8, v8, v9
	v_fmamk_f32 v8, v8, 0x3c800000, v52
	v_mul_f32_e32 v9, 0x4b800000, v8
	v_cmp_gt_f32_e64 s[8:9], s24, v8
	s_waitcnt vmcnt(0)
	v_cvt_f32_i32_e32 v12, v12
	v_cndmask_b32_e64 v8, v8, v9, s[8:9]
	v_rsq_f32_e32 v8, v8
	s_nop 0
	v_mul_f32_e32 v9, 0x45800000, v8
	v_cndmask_b32_e64 v64, v8, v9, s[8:9]
	v_pk_mul_f32 v[8:9], v[26:27], v[64:65] op_sel_hi:[1,0]
	v_pk_mul_f32 v[26:27], v[30:31], v[64:65] op_sel_hi:[1,0]
	v_pk_mul_f32 v[8:9], v[8:9], v[34:35]
	ds_bpermute_b32 v17, v43, v8
	v_pk_mul_f32 v[10:11], v[28:29], v[64:65] op_sel_hi:[1,0]
	v_pk_mul_f32 v[28:29], v[26:27], v[60:61]
	v_pk_mul_f32 v[26:27], v[32:33], v[64:65] op_sel_hi:[1,0]
	v_pk_mul_f32 v[10:11], v[10:11], v[58:59]
	v_pk_mul_f32 v[26:27], v[26:27], v[62:63]
	s_and_saveexec_b64 s[8:9], vcc
	s_cbranch_execz .LBB0_409
	v_mul_f32_e32 v30, 0.15915494, v12
	v_rndne_f32_e32 v30, v30
	v_fmamk_f32 v31, v30, 0xc0c90fdb, v12
	v_fmac_f32_e32 v31, 0x343bbd2e, v30
	v_mul_f32_e32 v30, 0.15915494, v31
	v_sin_f32_e32 v31, v30
	v_cos_f32_e32 v30, v30
	s_waitcnt lgkmcnt(0)
	v_mul_f32_e32 v17, v31, v17
	v_cndmask_b32_e64 v17, v17, -v17, s[0:1]
	v_fmac_f32_e32 v17, v30, v8
	v_mov_b32_e32 v8, v17

.LBB0_423:
	s_or_b64 exec, exec, s[8:9]
	v_cndmask_b32_e64 v12, 1.0, v53, s[6:7]
	v_mul_f32_e32 v8, v12, v8
	v_mul_f32_e32 v9, v12, v9
	v_cvt_pk_bf16_f32 v8, v8, v9
	v_mul_f32_e32 v9, v12, v10
	v_mul_f32_e32 v10, v12, v11
	v_cvt_pk_bf16_f32 v9, v9, v10
	v_mul_f32_e32 v10, v12, v28
	v_mul_f32_e32 v11, v12, v29
	v_cvt_pk_bf16_f32 v10, v10, v11
	v_mul_f32_e32 v11, v12, v26
	v_mul_f32_e32 v12, v12, v27
	v_cvt_pk_bf16_f32 v11, v11, v12
	v_add_u32_e32 v12, s21, v56
	v_cmp_gt_i32_e64 s[6:7], s18, v12
	s_and_saveexec_b64 s[8:9], s[6:7]
	s_cbranch_execz .LBB0_425
	global_store_dwordx4 v[24:25], v[8:11], off sc0 sc1

.LBB0_441:
	s_or_b64 exec, exec, s[6:7]
	v_cndmask_b32_e64 v17, 1.0, v53, s[4:5]
	v_mul_f32_e32 v4, v17, v4
	v_mul_f32_e32 v5, v17, v5
	v_cvt_pk_bf16_f32 v4, v4, v5
	v_mul_f32_e32 v5, v17, v6
	v_mul_f32_e32 v6, v17, v7
	v_cvt_pk_bf16_f32 v5, v5, v6
	v_mul_f32_e32 v6, v17, v10
	v_mul_f32_e32 v7, v17, v11
	v_cvt_pk_bf16_f32 v6, v6, v7
	v_mul_f32_e32 v7, v17, v8
	v_mul_f32_e32 v8, v17, v9
	v_cvt_pk_bf16_f32 v7, v7, v8
	v_add_u32_e32 v8, s19, v12
	v_cmp_gt_i32_e64 s[4:5], s18, v8
	s_and_saveexec_b64 s[6:7], s[4:5]
	s_cbranch_execz .LBB0_443
	global_store_dwordx4 v[22:23], v[4:7], off sc0 sc1

.LBB0_459:
	s_or_b64 exec, exec, s[4:5]
	v_cndmask_b32_e64 v9, 1.0, v53, s[2:3]
	v_mul_f32_e32 v0, v9, v0
	v_mul_f32_e32 v1, v9, v1
	v_cvt_pk_bf16_f32 v0, v0, v1
	v_mul_f32_e32 v1, v9, v2
	v_mul_f32_e32 v2, v9, v3
	v_cvt_pk_bf16_f32 v1, v1, v2
	v_mul_f32_e32 v2, v9, v6
	v_mul_f32_e32 v3, v9, v7
	v_cvt_pk_bf16_f32 v2, v2, v3
	v_mul_f32_e32 v3, v9, v4
	v_mul_f32_e32 v4, v9, v5
	v_cvt_pk_bf16_f32 v3, v3, v4
	v_add_u32_e32 v4, s19, v8
	v_cmp_gt_i32_e64 s[2:3], s18, v4
	s_and_saveexec_b64 s[4:5], s[2:3]
	s_cbranch_execz .LBB0_390
	global_store_dwordx4 v[20:21], v[0:3], off sc0 sc1
	s_branch .LBB0_390

.LBB0_536:
	v_lshl_or_b32 v146, s1, 8, v139
	s_ashr_i32 s1, s0, 31
	s_lshl_b64 s[0:1], s[0:1], 22
	s_add_u32 s0, s50, s0
	v_lshl_add_u32 v148, s8, 8, v137
	s_addc_u32 s1, s51, s1
	v_ashrrev_i32_e32 v147, 31, v146
	v_ashrrev_i32_e32 v149, 31, v148
	v_lshl_add_u64 v[146:147], v[146:147], 2, s[0:1]
	v_lshlrev_b64 v[150:151], 12, v[148:149]
	v_lshl_add_u64 v[150:151], v[146:147], 0, v[150:151]
	global_store_dwordx4 v[150:151], v[124:127], off sc0 sc1
	global_store_dwordx4 v[150:151], v[120:123], off offset:64 sc0 sc1
	global_store_dwordx4 v[150:151], v[108:111], off offset:512 sc0 sc1
	global_store_dwordx4 v[150:151], v[100:103], off offset:576 sc0 sc1
	s_mov_b64 s[0:1], -1
	s_nop 0
	v_or_b32_e32 v100, 16, v148
	v_ashrrev_i32_e32 v101, 31, v100
	v_lshlrev_b64 v[100:101], 12, v[100:101]
	v_lshl_add_u64 v[100:101], v[146:147], 0, v[100:101]
	global_store_dwordx4 v[100:101], v[116:119], off sc0 sc1
	global_store_dwordx4 v[100:101], v[112:115], off offset:64 sc0 sc1
	global_store_dwordx4 v[100:101], v[92:95], off offset:512 sc0 sc1
	global_store_dwordx4 v[100:101], v[84:87], off offset:576 sc0 sc1
	s_nop 1
	v_or_b32_e32 v84, 32, v148
	v_ashrrev_i32_e32 v85, 31, v84
	v_lshlrev_b64 v[84:85], 12, v[84:85]
	v_lshl_add_u64 v[84:85], v[146:147], 0, v[84:85]
	global_store_dwordx4 v[84:85], v[104:107], off sc0 sc1
	global_store_dwordx4 v[84:85], v[96:99], off offset:64 sc0 sc1
	global_store_dwordx4 v[84:85], v[76:79], off offset:512 sc0 sc1
	global_store_dwordx4 v[84:85], v[72:75], off offset:576 sc0 sc1
	s_nop 1
	v_or_b32_e32 v72, 48, v148
	v_ashrrev_i32_e32 v73, 31, v72
	v_lshlrev_b64 v[72:73], 12, v[72:73]
	v_lshl_add_u64 v[72:73], v[146:147], 0, v[72:73]
	global_store_dwordx4 v[72:73], v[88:91], off sc0 sc1
	global_store_dwordx4 v[72:73], v[80:83], off offset:64 sc0 sc1
	global_store_dwordx4 v[72:73], v[68:71], off offset:512 sc0 sc1
	global_store_dwordx4 v[72:73], v[64:67], off offset:576 sc0 sc1
	s_nop 1
	v_add_co_u32_e32 v66, vcc, s57, v150
	v_lshl_add_u64 v[64:65], v[150:151], 0, s[2:3]
	s_nop 0
	v_addc_co_u32_e32 v67, vcc, 0, v151, vcc
	global_store_dwordx4 v[66:67], v[60:63], off sc0 sc1
	global_store_dwordx4 v[64:65], v[56:59], off offset:64 sc0 sc1
	global_store_dwordx4 v[64:65], v[44:47], off offset:512 sc0 sc1
	global_store_dwordx4 v[64:65], v[36:39], off offset:576 sc0 sc1
	s_nop 1
	v_add_co_u32_e32 v38, vcc, s58, v150
	v_lshl_add_u64 v[36:37], v[150:151], 0, s[12:13]
	s_nop 0
	v_addc_co_u32_e32 v39, vcc, 0, v151, vcc
	global_store_dwordx4 v[38:39], v[52:55], off sc0 sc1
	global_store_dwordx4 v[36:37], v[48:51], off offset:64 sc0 sc1
	global_store_dwordx4 v[36:37], v[28:31], off offset:512 sc0 sc1
	global_store_dwordx4 v[36:37], v[20:23], off offset:576 sc0 sc1
	s_nop 1
	v_add_co_u32_e32 v22, vcc, s59, v150
	v_lshl_add_u64 v[20:21], v[150:151], 0, s[14:15]
	s_nop 0
	v_addc_co_u32_e32 v23, vcc, 0, v151, vcc
	global_store_dwordx4 v[22:23], v[40:43], off sc0 sc1
	global_store_dwordx4 v[20:21], v[32:35], off offset:64 sc0 sc1
	global_store_dwordx4 v[20:21], v[12:15], off offset:512 sc0 sc1
	global_store_dwordx4 v[20:21], v[8:11], off offset:576 sc0 sc1
	s_nop 1
	v_add_co_u32_e32 v10, vcc, 0xb0000, v150
	v_lshl_add_u64 v[8:9], v[150:151], 0, s[16:17]
	s_nop 0
	v_addc_co_u32_e32 v11, vcc, 0, v151, vcc
	s_andn2_b64 vcc, exec, s[20:21]
	global_store_dwordx4 v[10:11], v[24:27], off sc0 sc1
	global_store_dwordx4 v[8:9], v[16:19], off offset:64 sc0 sc1
	global_store_dwordx4 v[8:9], v[4:7], off offset:512 sc0 sc1
	global_store_dwordx4 v[8:9], v[0:3], off offset:576 sc0 sc1
	s_cbranch_vccnz .LBB0_525
	s_andn2_b64 vcc, exec, s[4:5]
	s_cbranch_vccnz .LBB0_524
	s_barrier
	s_branch .LBB0_524

.LBB0_542:
	v_bfe_u32 v0, v2, 5, 4
	v_ashrrev_i32_e32 v6, 1, v2
	v_and_or_b32 v5, v4, s10, v3
	v_and_or_b32 v6, v6, s11, v0
	v_lshlrev_b32_e32 v0, 2, v5
	v_ashrrev_i32_e32 v7, 31, v6
	v_lshl_add_u64 v[10:11], s[2:3], 0, v[0:1]
	v_or_b32_e32 v8, 16, v6
	v_lshlrev_b32_e32 v0, 1, v5
	v_lshlrev_b64 v[40:41], 15, v[6:7]
	v_or_b32_e32 v12, 32, v6
	v_or_b32_e32 v14, 48, v6
	v_or_b32_e32 v16, 64, v6
	v_or_b32_e32 v18, 0x50, v6
	v_or_b32_e32 v20, 0x60, v6
	v_or_b32_e32 v22, 0x70, v6
	v_or_b32_e32 v24, 0x80, v6
	v_or_b32_e32 v26, 0x90, v6
	v_or_b32_e32 v28, 0xa0, v6
	v_or_b32_e32 v30, 0xb0, v6
	v_or_b32_e32 v32, 0xc0, v6
	v_or_b32_e32 v34, 0xd0, v6
	v_or_b32_e32 v36, 0xe0, v6
	v_or_b32_e32 v38, 0xf0, v6
	v_lshl_add_u64 v[42:43], v[6:7], 2, s[4:5]
	v_ashrrev_i32_e32 v9, 31, v8
	v_lshl_add_u64 v[44:45], s[82:83], 0, v[0:1]
	v_lshlrev_b64 v[6:7], 14, v[6:7]
	v_lshl_add_u64 v[40:41], v[10:11], 0, v[40:41]
	v_lshlrev_b64 v[46:47], 15, v[8:9]
	v_lshl_add_u64 v[48:49], v[8:9], 2, s[4:5]
	v_lshl_add_u64 v[102:103], v[44:45], 0, v[6:7]
	v_lshlrev_b64 v[104:105], 14, v[8:9]
	global_load_dwordx4 v[6:9], v[40:41], off
	global_load_dword v0, v[42:43], off
	v_ashrrev_i32_e32 v13, 31, v12
	v_ashrrev_i32_e32 v15, 31, v14
	v_ashrrev_i32_e32 v17, 31, v16
	v_ashrrev_i32_e32 v19, 31, v18
	v_ashrrev_i32_e32 v21, 31, v20
	v_ashrrev_i32_e32 v23, 31, v22
	v_ashrrev_i32_e32 v25, 31, v24
	v_ashrrev_i32_e32 v27, 31, v26
	v_ashrrev_i32_e32 v29, 31, v28
	v_ashrrev_i32_e32 v31, 31, v30
	v_ashrrev_i32_e32 v33, 31, v32
	v_ashrrev_i32_e32 v35, 31, v34
	v_ashrrev_i32_e32 v37, 31, v36
	v_ashrrev_i32_e32 v39, 31, v38
	v_lshlrev_b64 v[50:51], 15, v[12:13]
	v_lshlrev_b64 v[54:55], 15, v[14:15]
	v_lshlrev_b64 v[58:59], 15, v[16:17]
	v_lshlrev_b64 v[62:63], 15, v[18:19]
	v_lshl_add_u64 v[52:53], v[12:13], 2, s[4:5]
	v_lshl_add_u64 v[56:57], v[14:15], 2, s[4:5]
	v_lshl_add_u64 v[60:61], v[16:17], 2, s[4:5]
	v_lshl_add_u64 v[64:65], v[18:19], 2, s[4:5]
	v_lshlrev_b64 v[66:67], 15, v[20:21]
	v_lshl_add_u64 v[68:69], v[20:21], 2, s[4:5]
	v_lshlrev_b64 v[70:71], 15, v[22:23]
	v_lshl_add_u64 v[72:73], v[22:23], 2, s[4:5]
	v_lshlrev_b64 v[74:75], 15, v[24:25]
	v_lshl_add_u64 v[76:77], v[24:25], 2, s[4:5]
	v_lshlrev_b64 v[78:79], 15, v[26:27]
	v_lshl_add_u64 v[80:81], v[26:27], 2, s[4:5]
	v_lshlrev_b64 v[82:83], 15, v[28:29]
	v_lshl_add_u64 v[84:85], v[28:29], 2, s[4:5]
	v_lshlrev_b64 v[86:87], 15, v[30:31]
	v_lshl_add_u64 v[88:89], v[30:31], 2, s[4:5]
	v_lshlrev_b64 v[90:91], 15, v[32:33]
	v_lshl_add_u64 v[92:93], v[32:33], 2, s[4:5]
	v_lshlrev_b64 v[94:95], 15, v[34:35]
	v_lshl_add_u64 v[96:97], v[34:35], 2, s[4:5]
	v_lshlrev_b64 v[98:99], 15, v[36:37]
	v_lshl_add_u64 v[100:101], v[36:37], 2, s[4:5]
	v_lshlrev_b64 v[12:13], 14, v[12:13]
	v_lshlrev_b64 v[14:15], 14, v[14:15]
	v_lshlrev_b64 v[16:17], 14, v[16:17]
	v_lshlrev_b64 v[18:19], 14, v[18:19]
	v_lshlrev_b64 v[20:21], 14, v[20:21]
	v_lshlrev_b64 v[22:23], 14, v[22:23]
	v_lshlrev_b64 v[24:25], 14, v[24:25]
	v_lshlrev_b64 v[26:27], 14, v[26:27]
	v_lshlrev_b64 v[28:29], 14, v[28:29]
	v_lshlrev_b64 v[30:31], 14, v[30:31]
	v_lshlrev_b64 v[32:33], 14, v[32:33]
	v_lshlrev_b64 v[34:35], 14, v[34:35]
	v_lshlrev_b64 v[36:37], 14, v[36:37]
	v_lshlrev_b64 v[38:39], 14, v[38:39]
	v_lshl_add_u64 v[40:41], v[10:11], 0, v[46:47]
	v_lshl_add_u64 v[50:51], v[10:11], 0, v[50:51]
	v_lshl_add_u64 v[54:55], v[10:11], 0, v[54:55]
	v_lshl_add_u64 v[58:59], v[10:11], 0, v[58:59]
	v_lshl_add_u64 v[62:63], v[10:11], 0, v[62:63]
	v_lshl_add_u64 v[66:67], v[10:11], 0, v[66:67]
	v_lshl_add_u64 v[70:71], v[10:11], 0, v[70:71]
	v_lshl_add_u64 v[74:75], v[10:11], 0, v[74:75]
	v_lshl_add_u64 v[78:79], v[10:11], 0, v[78:79]
	v_lshl_add_u64 v[82:83], v[10:11], 0, v[82:83]
	v_lshl_add_u64 v[86:87], v[10:11], 0, v[86:87]
	v_lshl_add_u64 v[90:91], v[10:11], 0, v[90:91]
	v_lshl_add_u64 v[94:95], v[10:11], 0, v[94:95]
	v_lshl_add_u64 v[98:99], v[10:11], 0, v[98:99]
	v_lshl_add_u64 v[104:105], v[44:45], 0, v[104:105]
	v_lshl_add_u64 v[106:107], v[44:45], 0, v[12:13]
	v_lshl_add_u64 v[108:109], v[44:45], 0, v[14:15]
	v_lshl_add_u64 v[110:111], v[44:45], 0, v[16:17]
	v_lshl_add_u64 v[112:113], v[44:45], 0, v[18:19]
	v_lshl_add_u64 v[114:115], v[44:45], 0, v[20:21]
	v_lshl_add_u64 v[116:117], v[44:45], 0, v[22:23]
	v_lshl_add_u64 v[118:119], v[44:45], 0, v[24:25]
	v_lshl_add_u64 v[120:121], v[44:45], 0, v[26:27]
	v_lshl_add_u64 v[122:123], v[44:45], 0, v[28:29]
	v_lshl_add_u64 v[124:125], v[44:45], 0, v[30:31]
	v_lshl_add_u64 v[126:127], v[44:45], 0, v[32:33]
	v_lshl_add_u64 v[128:129], v[44:45], 0, v[34:35]
	v_lshl_add_u64 v[130:131], v[44:45], 0, v[36:37]
	v_lshl_add_u64 v[132:133], v[44:45], 0, v[38:39]
	global_load_dword v5, v[48:49], off
	global_load_dword v134, v[52:53], off
	global_load_dword v135, v[56:57], off
	global_load_dword v136, v[60:61], off
	global_load_dword v137, v[64:65], off
	global_load_dword v138, v[68:69], off
	global_load_dword v139, v[72:73], off
	global_load_dword v140, v[76:77], off
	global_load_dword v141, v[80:81], off
	global_load_dword v142, v[84:85], off
	global_load_dword v143, v[88:89], off
	global_load_dword v144, v[92:93], off
	global_load_dword v146, v[96:97], off
	global_load_dword v148, v[100:101], off
	global_load_dwordx4 v[10:13], v[40:41], off
	global_load_dwordx4 v[14:17], v[50:51], off
	global_load_dwordx4 v[18:21], v[54:55], off
	global_load_dwordx4 v[22:25], v[58:59], off
	global_load_dwordx4 v[26:29], v[62:63], off
	global_load_dwordx4 v[30:33], v[66:67], off
	global_load_dwordx4 v[34:37], v[70:71], off
	global_load_dwordx4 v[38:41], v[74:75], off
	global_load_dwordx4 v[42:45], v[78:79], off
	global_load_dwordx4 v[46:49], v[82:83], off
	global_load_dwordx4 v[50:53], v[86:87], off
	global_load_dwordx4 v[54:57], v[90:91], off
	global_load_dwordx4 v[58:61], v[94:95], off
	global_load_dwordx4 v[62:65], v[98:99], off
	v_cvt_pk_bf16_f32 v66, v1, v1
	v_cvt_pk_bf16_f32 v67, v1, v1
	s_waitcnt vmcnt(0)
	v_mul_f32_e32 v0, 0x3fb8aa3b, v0
	global_store_dwordx2 v[102:103], v[66:67], off sc0 sc1
	v_exp_f32_e32 v67, v0
	v_add_u32_e32 v2, s8, v2
	v_cmp_lt_i32_e32 vcc, s12, v2
	v_add_u32_e32 v4, s9, v4
	v_mul_f32_e32 v92, 0, v67
	v_pk_add_f32 v[6:7], v[6:7], v[92:93] op_sel_hi:[1,0]
	v_pk_add_f32 v[8:9], v[8:9], v[92:93] op_sel_hi:[1,0]
	v_cvt_pk_bf16_f32 v92, v6, v7
	s_or_b64 s[6:7], vcc, s[6:7]
	v_cvt_pk_bf16_f32 v93, v8, v9
	global_store_dwordx2 v[104:105], v[92:93], off sc0 sc1
	v_mul_f32_e32 v0, 0x3fb8aa3b, v5
	v_mul_f32_e32 v5, 0x3fb8aa3b, v134
	v_exp_f32_e32 v0, v0
	v_mul_f32_e32 v68, 0x3fb8aa3b, v135
	v_exp_f32_e32 v66, v5
	v_mul_f32_e32 v69, 0x3fb8aa3b, v136
	v_exp_f32_e32 v68, v68
	v_mul_f32_e32 v71, 0x3fb8aa3b, v137
	v_exp_f32_e32 v70, v69
	v_mul_f32_e32 v73, 0x3fb8aa3b, v138
	v_exp_f32_e32 v72, v71
	v_mul_f32_e32 v75, 0x3fb8aa3b, v139
	v_exp_f32_e32 v74, v73
	v_mul_f32_e32 v77, 0x3fb8aa3b, v140
	v_pk_fma_f32 v[6:7], v[6:7], v[0:1], v[10:11] op_sel_hi:[1,0,1]
	v_pk_fma_f32 v[8:9], v[8:9], v[0:1], v[12:13] op_sel_hi:[1,0,1]
	v_cvt_pk_bf16_f32 v10, v6, v7
	v_exp_f32_e32 v76, v75
	v_cvt_pk_bf16_f32 v11, v8, v9
	global_store_dwordx2 v[106:107], v[10:11], off sc0 sc1
	v_mul_f32_e32 v79, 0x3fb8aa3b, v141
	v_exp_f32_e32 v78, v77
	v_mul_f32_e32 v81, 0x3fb8aa3b, v142
	v_exp_f32_e32 v80, v79
	v_mul_f32_e32 v83, 0x3fb8aa3b, v143
	v_exp_f32_e32 v82, v81
	v_mul_f32_e32 v85, 0x3fb8aa3b, v144
	v_exp_f32_e32 v84, v83
	v_mul_f32_e32 v87, 0x3fb8aa3b, v146
	v_exp_f32_e32 v86, v85
	v_pk_fma_f32 v[6:7], v[6:7], v[66:67], v[14:15] op_sel_hi:[1,0,1]
	v_pk_fma_f32 v[8:9], v[8:9], v[66:67], v[16:17] op_sel_hi:[1,0,1]
	v_cvt_pk_bf16_f32 v10, v6, v7
	v_pk_fma_f32 v[6:7], v[6:7], v[68:69], v[18:19] op_sel_hi:[1,0,1]
	v_cvt_pk_bf16_f32 v11, v8, v9
	v_pk_fma_f32 v[8:9], v[8:9], v[68:69], v[20:21] op_sel_hi:[1,0,1]
	global_store_dwordx2 v[108:109], v[10:11], off sc0 sc1
	v_cvt_pk_bf16_f32 v10, v6, v7
	v_pk_fma_f32 v[6:7], v[6:7], v[70:71], v[22:23] op_sel_hi:[1,0,1]
	v_cvt_pk_bf16_f32 v11, v8, v9
	v_pk_fma_f32 v[8:9], v[8:9], v[70:71], v[24:25] op_sel_hi:[1,0,1]
	global_store_dwordx2 v[110:111], v[10:11], off sc0 sc1
	v_cvt_pk_bf16_f32 v10, v6, v7
	v_pk_fma_f32 v[6:7], v[6:7], v[72:73], v[26:27] op_sel_hi:[1,0,1]
	v_cvt_pk_bf16_f32 v11, v8, v9
	v_pk_fma_f32 v[8:9], v[8:9], v[72:73], v[28:29] op_sel_hi:[1,0,1]
	global_store_dwordx2 v[112:113], v[10:11], off sc0 sc1
	v_cvt_pk_bf16_f32 v10, v6, v7
	v_pk_fma_f32 v[6:7], v[6:7], v[74:75], v[30:31] op_sel_hi:[1,0,1]
	v_cvt_pk_bf16_f32 v11, v8, v9
	v_pk_fma_f32 v[8:9], v[8:9], v[74:75], v[32:33] op_sel_hi:[1,0,1]
	global_store_dwordx2 v[114:115], v[10:11], off sc0 sc1
	v_cvt_pk_bf16_f32 v10, v6, v7
	v_pk_fma_f32 v[6:7], v[6:7], v[76:77], v[34:35] op_sel_hi:[1,0,1]
	v_cvt_pk_bf16_f32 v11, v8, v9
	v_pk_fma_f32 v[8:9], v[8:9], v[76:77], v[36:37] op_sel_hi:[1,0,1]
	global_store_dwordx2 v[116:117], v[10:11], off sc0 sc1
	v_cvt_pk_bf16_f32 v10, v6, v7
	v_pk_fma_f32 v[6:7], v[6:7], v[78:79], v[38:39] op_sel_hi:[1,0,1]
	v_mul_f32_e32 v89, 0x3fb8aa3b, v148
	v_exp_f32_e32 v88, v87
	v_cvt_pk_bf16_f32 v11, v8, v9
	v_pk_fma_f32 v[8:9], v[8:9], v[78:79], v[40:41] op_sel_hi:[1,0,1]
	global_store_dwordx2 v[118:119], v[10:11], off sc0 sc1
	v_cvt_pk_bf16_f32 v10, v6, v7
	v_pk_fma_f32 v[6:7], v[6:7], v[80:81], v[42:43] op_sel_hi:[1,0,1]
	v_exp_f32_e32 v90, v89
	v_cvt_pk_bf16_f32 v11, v8, v9
	v_pk_fma_f32 v[8:9], v[8:9], v[80:81], v[44:45] op_sel_hi:[1,0,1]
	global_store_dwordx2 v[120:121], v[10:11], off sc0 sc1
	v_cvt_pk_bf16_f32 v10, v6, v7
	v_pk_fma_f32 v[6:7], v[6:7], v[82:83], v[46:47] op_sel_hi:[1,0,1]
	v_cvt_pk_bf16_f32 v11, v8, v9
	v_pk_fma_f32 v[8:9], v[8:9], v[82:83], v[48:49] op_sel_hi:[1,0,1]
	global_store_dwordx2 v[122:123], v[10:11], off sc0 sc1
	v_cvt_pk_bf16_f32 v10, v6, v7
	v_pk_fma_f32 v[6:7], v[6:7], v[84:85], v[50:51] op_sel_hi:[1,0,1]
	v_cvt_pk_bf16_f32 v11, v8, v9
	v_pk_fma_f32 v[8:9], v[8:9], v[84:85], v[52:53] op_sel_hi:[1,0,1]
	global_store_dwordx2 v[124:125], v[10:11], off sc0 sc1
	v_cvt_pk_bf16_f32 v10, v6, v7
	v_pk_fma_f32 v[6:7], v[6:7], v[86:87], v[54:55] op_sel_hi:[1,0,1]
	v_cvt_pk_bf16_f32 v11, v8, v9
	v_pk_fma_f32 v[8:9], v[8:9], v[86:87], v[56:57] op_sel_hi:[1,0,1]
	global_store_dwordx2 v[126:127], v[10:11], off sc0 sc1
	v_cvt_pk_bf16_f32 v10, v6, v7
	v_pk_fma_f32 v[6:7], v[6:7], v[88:89], v[58:59] op_sel_hi:[1,0,1]
	v_cvt_pk_bf16_f32 v11, v8, v9
	v_pk_fma_f32 v[8:9], v[8:9], v[88:89], v[60:61] op_sel_hi:[1,0,1]
	global_store_dwordx2 v[128:129], v[10:11], off sc0 sc1
	v_cvt_pk_bf16_f32 v10, v6, v7
	v_pk_fma_f32 v[6:7], v[6:7], v[90:91], v[62:63] op_sel_hi:[1,0,1]
	v_cvt_pk_bf16_f32 v11, v8, v9
	v_pk_fma_f32 v[8:9], v[8:9], v[90:91], v[64:65] op_sel_hi:[1,0,1]
	global_store_dwordx2 v[130:131], v[10:11], off sc0 sc1
	v_cvt_pk_bf16_f32 v6, v6, v7
	v_cvt_pk_bf16_f32 v7, v8, v9
	global_store_dwordx2 v[132:133], v[6:7], off sc0 sc1
	s_andn2_b64 exec, exec, s[6:7]
	s_cbranch_execnz .LBB0_542

.LBB0_875:
	v_mov_b32_e32 v153, v34
	v_mov_b32_e32 v194, v35
	ds_read_b128 v[32:35], v152
	ds_read_b128 v[140:143], v152 offset:32
	ds_read_b128 v[136:139], v152 offset:64
	ds_read_b128 v[132:135], v152 offset:96
	s_waitcnt lgkmcnt(3)
	v_mfma_f32_32x32x16_bf16 v[32:47], v[32:35], v[76:79], 0
	v_add_u32_e32 v195, 27, v192
	v_add_u32_e32 v196, v146, v151
	v_add_u32_e32 v197, 25, v192
	v_add_u32_e32 v198, 24, v192
	v_cmp_lt_u32_e32 vcc, s76, v196
	v_cmp_gt_u32_e64 s[36:37], s68, v195
	v_add_u32_e32 v199, 19, v192
	s_waitcnt lgkmcnt(2)
	v_mfma_f32_32x32x16_bf16 v[32:47], v[140:143], v[80:83], v[32:47]
	v_add_u32_e32 v200, 18, v192
	v_cmp_gt_u32_e64 s[6:7], s68, v197
	v_cmp_gt_u32_e64 s[8:9], s68, v198
	v_add_u32_e32 v201, 17, v192
	v_add_u32_e32 v202, 16, v192
	v_cmp_gt_u32_e64 s[10:11], s68, v199
	v_cmp_gt_u32_e64 s[12:13], s68, v200
	s_waitcnt lgkmcnt(1)
	v_mfma_f32_32x32x16_bf16 v[32:47], v[136:139], v[84:87], v[32:47]
	v_add_u32_e32 v203, 11, v192
	v_add_u32_e32 v204, 10, v192
	v_cmp_gt_u32_e64 s[14:15], s68, v201
	v_cmp_gt_u32_e64 s[16:17], s68, v202
	v_add_u32_e32 v205, 9, v192
	v_add_u32_e32 v206, 8, v192
	v_cmp_gt_u32_e64 s[18:19], s68, v203
	s_waitcnt lgkmcnt(0)
	v_mfma_f32_32x32x16_bf16 v[32:47], v[132:135], v[88:91], v[32:47]
	v_cmp_gt_u32_e64 s[20:21], s68, v204
	v_add_u32_e32 v207, 3, v192
	v_add_u32_e32 v208, 2, v192
	v_cmp_gt_u32_e64 s[22:23], s68, v205
	v_cmp_gt_u32_e64 s[24:25], s68, v206
	v_add_u32_e32 v209, 1, v192
	v_cmp_gt_u32_e64 s[26:27], s68, v207
	s_nop 4
	v_cndmask_b32_e64 v32, v190, v32, s[36:37]
	v_cndmask_b32_e32 v33, v190, v33, vcc
	v_cndmask_b32_e64 v132, v190, v34, s[6:7]
	v_cndmask_b32_e64 v35, v190, v35, s[8:9]
	v_max3_f32 v34, v32, s69, v33
	v_cndmask_b32_e64 v36, v190, v36, s[10:11]
	v_cndmask_b32_e64 v37, v190, v37, s[12:13]
	v_max3_f32 v34, v34, v132, v35
	v_cndmask_b32_e64 v38, v190, v38, s[14:15]
	v_cndmask_b32_e64 v39, v190, v39, s[16:17]
	v_max3_f32 v34, v34, v36, v37
	v_cndmask_b32_e64 v40, v190, v40, s[18:19]
	v_cndmask_b32_e64 v41, v190, v41, s[20:21]
	v_max3_f32 v34, v34, v38, v39
	v_cmp_gt_u32_e64 s[28:29], s68, v208
	v_cndmask_b32_e64 v42, v190, v42, s[22:23]
	v_cndmask_b32_e64 v43, v190, v43, s[24:25]
	v_max3_f32 v34, v34, v40, v41
	v_cmp_gt_u32_e64 s[30:31], s68, v209
	v_cmp_gt_u32_e64 s[34:35], s68, v192
	v_cndmask_b32_e64 v44, v190, v44, s[26:27]
	v_cndmask_b32_e64 v45, v190, v45, s[28:29]
	v_max3_f32 v34, v34, v42, v43
	v_cndmask_b32_e64 v46, v190, v46, s[30:31]
	v_cndmask_b32_e64 v47, v190, v47, s[34:35]
	v_max3_f32 v34, v34, v44, v45
	v_max3_f32 v34, v34, v46, v47
	ds_bpermute_b32 v133, v73, v34
	v_add_u32_e32 v210, v146, v193
	v_add_u32_e32 v211, 8, v210
	v_add_u32_e32 v212, 16, v210
	v_add_u32_e32 v213, 24, v210
	s_waitcnt lgkmcnt(0)
	v_max3_f32 v34, v153, v34, v133
	v_sub_f32_e32 v32, v32, v34
	v_sub_f32_e32 v133, v153, v34
	v_sub_f32_e32 v33, v33, v34
	v_mul_f32_e32 v32, 0x3fb8aa3b, v32
	v_sub_f32_e32 v132, v132, v34
	v_mul_f32_e32 v133, 0x3fb8aa3b, v133
	v_mul_f32_e32 v33, 0x3fb8aa3b, v33
	v_exp_f32_e32 v134, v32
	v_sub_f32_e32 v35, v35, v34
	v_mul_f32_e32 v132, 0x3fb8aa3b, v132
	v_exp_f32_e32 v33, v33
	v_exp_f32_e32 v32, v133
	v_sub_f32_e32 v36, v36, v34
	v_mul_f32_e32 v35, 0x3fb8aa3b, v35
	v_exp_f32_e32 v153, v132
	v_sub_f32_e32 v37, v37, v34
	v_mul_f32_e32 v36, 0x3fb8aa3b, v36
	v_exp_f32_e32 v35, v35
	v_xor_b32_e32 v214, v210, v172
	v_xor_b32_e32 v141, v211, v172
	v_xor_b32_e32 v142, v212, v172
	v_xor_b32_e32 v143, v213, v172
	v_sub_f32_e32 v38, v38, v34
	v_sub_f32_e32 v39, v39, v34
	v_sub_f32_e32 v40, v40, v34
	v_sub_f32_e32 v41, v41, v34
	v_sub_f32_e32 v42, v42, v34
	v_sub_f32_e32 v43, v43, v34
	v_sub_f32_e32 v44, v44, v34
	v_sub_f32_e32 v45, v45, v34
	v_sub_f32_e32 v46, v46, v34
	v_sub_f32_e32 v47, v47, v34
	v_mul_f32_e32 v37, 0x3fb8aa3b, v37
	v_exp_f32_e32 v195, v36
	v_add_f32_e32 v207, 0, v134
	v_xor_b32_e32 v210, v210, v174
	v_lshl_add_u32 v140, v214, 1, v171
	v_xor_b32_e32 v211, v211, v174
	v_xor_b32_e32 v136, v213, v174
	v_lshl_add_u32 v137, v141, 1, v171
	v_lshl_add_u32 v138, v142, 1, v171
	v_lshl_add_u32 v139, v143, 1, v171
	v_mul_f32_e32 v38, 0x3fb8aa3b, v38
	v_mul_f32_e32 v39, 0x3fb8aa3b, v39
	v_mul_f32_e32 v40, 0x3fb8aa3b, v40
	v_mul_f32_e32 v41, 0x3fb8aa3b, v41
	v_mul_f32_e32 v42, 0x3fb8aa3b, v42
	v_mul_f32_e32 v43, 0x3fb8aa3b, v43
	v_mul_f32_e32 v44, 0x3fb8aa3b, v44
	v_mul_f32_e32 v45, 0x3fb8aa3b, v45
	v_mul_f32_e32 v46, 0x3fb8aa3b, v46
	v_mul_f32_e32 v47, 0x3fb8aa3b, v47
	v_exp_f32_e32 v196, v37
	v_pk_mul_f32 v[16:17], v[16:17], v[32:33] op_sel_hi:[1,0]
	v_pk_mul_f32 v[0:1], v[0:1], v[32:33] op_sel_hi:[1,0]
	v_pk_mul_f32 v[18:19], v[18:19], v[32:33] op_sel_hi:[1,0]
	v_pk_mul_f32 v[2:3], v[2:3], v[32:33] op_sel_hi:[1,0]
	v_pk_mul_f32 v[20:21], v[20:21], v[32:33] op_sel_hi:[1,0]
	v_pk_mul_f32 v[4:5], v[4:5], v[32:33] op_sel_hi:[1,0]
	v_pk_mul_f32 v[22:23], v[22:23], v[32:33] op_sel_hi:[1,0]
	v_pk_mul_f32 v[6:7], v[6:7], v[32:33] op_sel_hi:[1,0]
	v_cvt_pk_bf16_f32 v36, v134, v33
	v_pk_mul_f32 v[24:25], v[24:25], v[32:33] op_sel_hi:[1,0]
	v_pk_mul_f32 v[26:27], v[26:27], v[32:33] op_sel_hi:[1,0]
	v_pk_mul_f32 v[28:29], v[28:29], v[32:33] op_sel_hi:[1,0]
	v_pk_mul_f32 v[30:31], v[30:31], v[32:33] op_sel_hi:[1,0]
	v_pk_mul_f32 v[8:9], v[8:9], v[32:33] op_sel_hi:[1,0]
	v_pk_mul_f32 v[10:11], v[10:11], v[32:33] op_sel_hi:[1,0]
	v_pk_mul_f32 v[12:13], v[12:13], v[32:33] op_sel_hi:[1,0]
	v_pk_mul_f32 v[14:15], v[14:15], v[32:33] op_sel_hi:[1,0]
	v_add_f32_e32 v33, v33, v207
	v_lshl_add_u32 v210, v210, 1, v173
	v_lshl_add_u32 v141, v211, 1, v173
	v_lshl_add_u32 v143, v136, 1, v173
	v_exp_f32_e32 v197, v38
	v_exp_f32_e32 v198, v39
	v_exp_f32_e32 v199, v40
	v_exp_f32_e32 v200, v41
	v_exp_f32_e32 v201, v42
	v_exp_f32_e32 v202, v43
	v_exp_f32_e32 v203, v44
	v_exp_f32_e32 v204, v45
	v_exp_f32_e32 v205, v46
	v_exp_f32_e32 v206, v47
	v_cvt_pk_bf16_f32 v37, v153, v35
	v_cvt_pk_bf16_f32 v38, v195, v196
	v_cvt_pk_bf16_f32 v39, v197, v198
	v_cvt_pk_bf16_f32 v40, v199, v200
	v_cvt_pk_bf16_f32 v41, v201, v202
	v_cvt_pk_bf16_f32 v42, v203, v204
	v_cvt_pk_bf16_f32 v43, v205, v206
	ds_read_b64 v[44:45], v140 offset:55296
	ds_read_b64 v[46:47], v137 offset:55296
	ds_read_b64 v[132:133], v138 offset:55296
	ds_read_b64 v[134:135], v139 offset:55296
	ds_read_b64 v[136:137], v210 offset:55296
	ds_read_b64 v[138:139], v141 offset:55296
	v_add_f32_e32 v33, v153, v33
	v_add_f32_e32 v33, v35, v33
	v_add_f32_e32 v33, v195, v33
	v_add_f32_e32 v33, v196, v33
	v_add_f32_e32 v33, v197, v33
	s_waitcnt lgkmcnt(4)
	v_mfma_f32_32x32x16_bf16 v[16:31], v[44:47], v[36:39], v[16:31]
	v_add_f32_e32 v33, v198, v33
	v_xor_b32_e32 v212, v212, v174
	v_add_f32_e32 v33, v199, v33
	v_lshl_add_u32 v142, v212, 1, v173
	v_add_f32_e32 v33, v200, v33
	ds_read_b64 v[44:45], v142 offset:55296
	ds_read_b64 v[46:47], v143 offset:55296
	v_add_f32_e32 v33, v201, v33
	s_waitcnt lgkmcnt(2)
	v_mfma_f32_32x32x16_bf16 v[0:15], v[136:139], v[36:39], v[0:15]
	v_add_f32_e32 v33, v202, v33
	v_add_f32_e32 v33, v203, v33
	v_add_f32_e32 v33, v204, v33
	v_add_f32_e32 v33, v205, v33
	v_add_f32_e32 v33, v206, v33
	ds_bpermute_b32 v35, v73, v33
	v_add_u32_e32 v75, 1, v75
	v_mfma_f32_32x32x16_bf16 v[16:31], v[132:135], v[40:43], v[16:31]
	v_cmp_lt_i32_e32 vcc, 3, v75
	v_add_u32_e32 v151, 32, v151
	s_waitcnt lgkmcnt(0)
	v_add_f32_e32 v35, v33, v35
	v_add_u32_e32 v193, 32, v193
	v_add_u32_e32 v152, 0x1200, v152
	s_or_b64 s[52:53], vcc, s[52:53]
	v_subrev_u32_e32 v192, 32, v192
	v_mfma_f32_32x32x16_bf16 v[0:15], v[44:47], v[40:43], v[0:15]
	v_fmac_f32_e32 v35, v194, v32
	s_andn2_b64 exec, exec, s[52:53]
	s_cbranch_execnz .LBB0_875
	s_or_b64 exec, exec, s[52:53]
	v_div_scale_f32 v32, s[6:7], v35, v35, 1.0
	v_rcp_f32_e32 v33, v32
	s_lshl_b32 s8, s51, 4
	s_and_b32 s9, s8, 0x1800
	s_bfe_u32 s8, s51, 0x40003
	v_fma_f32 v36, -v32, v33, 1.0
	v_fmac_f32_e32 v33, v36, v33
	v_div_scale_f32 v36, vcc, 1.0, v35, 1.0
	v_mul_f32_e32 v37, v36, v33
	v_fma_f32 v38, -v32, v37, v36
	v_fmac_f32_e32 v37, v38, v33
	s_ashr_i32 s51, s50, 31
	v_fma_f32 v32, -v32, v37, v36
	s_lshl_b64 s[6:7], s[50:51], 13
	v_mov_b32_e32 v75, v72
	v_div_fmas_f32 v32, v32, v33, v37
	s_or_b32 s6, s6, s9
	v_div_fixup_f32 v40, v32, v35, 1.0
	v_lshl_add_u64 v[32:33], s[6:7], 0, v[74:75]
	v_lshlrev_b64 v[36:37], 11, v[32:33]
	v_lshl_add_u64 v[36:37], s[42:43], 0, v[36:37]
	s_lshl_b32 s46, s8, 7
	v_mul_f32_e32 v16, v16, v40
	v_mul_f32_e32 v17, v17, v40
	v_lshl_add_u64 v[36:37], v[36:37], 0, s[46:47]
	v_lshlrev_b32_e32 v38, 1, v146
	v_mov_b32_e32 v39, v72
	v_cvt_pk_bf16_f32 v16, v16, v17
	v_mul_f32_e32 v17, v18, v40
	v_lshl_add_u64 v[36:37], v[36:37], 0, v[38:39]
	v_mul_f32_e32 v18, v19, v40
	v_cvt_pk_bf16_f32 v17, v17, v18
	global_store_dwordx2 v[36:37], v[16:17], off sc0 sc1
	v_mul_f32_e32 v16, v20, v40
	v_mul_f32_e32 v17, v21, v40
	v_cvt_pk_bf16_f32 v16, v16, v17
	v_mul_f32_e32 v17, v22, v40
	v_mul_f32_e32 v18, v23, v40
	v_cvt_pk_bf16_f32 v17, v17, v18
	global_store_dwordx2 v[36:37], v[16:17], off offset:16 sc0 sc1
	v_mul_f32_e32 v16, v24, v40
	v_mul_f32_e32 v17, v25, v40
	v_cvt_pk_bf16_f32 v16, v16, v17
	v_mul_f32_e32 v17, v26, v40
	v_mul_f32_e32 v18, v27, v40
	v_cvt_pk_bf16_f32 v17, v17, v18
	global_store_dwordx2 v[36:37], v[16:17], off offset:32 sc0 sc1
	v_mul_f32_e32 v16, v28, v40
	v_mul_f32_e32 v17, v29, v40
	v_cvt_pk_bf16_f32 v16, v16, v17
	v_mul_f32_e32 v17, v30, v40
	v_mul_f32_e32 v0, v0, v40
	v_mul_f32_e32 v1, v1, v40
	v_mul_f32_e32 v18, v31, v40
	v_cvt_pk_bf16_f32 v17, v17, v18
	global_store_dwordx2 v[36:37], v[16:17], off offset:48 sc0 sc1
	v_cvt_pk_bf16_f32 v0, v0, v1
	v_mul_f32_e32 v1, v2, v40
	v_mul_f32_e32 v2, v3, v40
	v_cvt_pk_bf16_f32 v1, v1, v2
	global_store_dwordx2 v[36:37], v[0:1], off offset:64 sc0 sc1
	v_mul_f32_e32 v0, v4, v40
	v_mul_f32_e32 v1, v5, v40
	v_cvt_pk_bf16_f32 v0, v0, v1
	v_mul_f32_e32 v1, v6, v40
	v_mul_f32_e32 v2, v7, v40
	v_cvt_pk_bf16_f32 v1, v1, v2
	global_store_dwordx2 v[36:37], v[0:1], off offset:80 sc0 sc1
	v_mul_f32_e32 v0, v8, v40
	v_mul_f32_e32 v1, v9, v40
	v_cvt_pk_bf16_f32 v0, v0, v1
	v_mul_f32_e32 v1, v10, v40
	v_mul_f32_e32 v2, v11, v40
	v_cvt_pk_bf16_f32 v1, v1, v2
	global_store_dwordx2 v[36:37], v[0:1], off offset:96 sc0 sc1
	v_mul_f32_e32 v0, v12, v40
	v_mul_f32_e32 v1, v13, v40
	v_cvt_pk_bf16_f32 v0, v0, v1
	v_mul_f32_e32 v1, v14, v40
	v_mul_f32_e32 v2, v15, v40
	v_cvt_pk_bf16_f32 v1, v1, v2
	global_store_dwordx2 v[36:37], v[0:1], off offset:112 sc0 sc1
	s_and_saveexec_b64 s[6:7], s[2:3]
	s_cbranch_execz .LBB0_727
	v_cmp_gt_f32_e32 vcc, s77, v35
	s_lshl_b32 s46, s8, 2
	s_nop 0
	v_cndmask_b32_e64 v0, 0, 32, vcc
	v_ldexp_f32 v0, v35, v0
	v_log_f32_e32 v0, v0
	v_cndmask_b32_e32 v1, 0, v191, vcc
	v_mul_f32_e32 v2, 0x3f317217, v0
	v_fma_f32 v2, v0, s78, -v2
	v_fmac_f32_e32 v2, 0x3377d1cf, v0
	v_fmac_f32_e32 v2, 0x3f317217, v0
	v_cmp_lt_f32_e64 vcc, |v0|, s79
	s_nop 1
	v_cndmask_b32_e32 v0, v0, v2, vcc
	v_sub_f32_e32 v0, v0, v1
	v_add_f32_e32 v2, v34, v0
	v_lshlrev_b64 v[0:1], 6, v[32:33]
	v_lshl_add_u64 v[0:1], s[44:45], 0, v[0:1]
	v_lshl_add_u64 v[0:1], v[0:1], 0, s[46:47]
	global_store_dword v[0:1], v2, off sc0 sc1
	s_branch .LBB0_727

.LBB0_937:
	s_or_b64 exec, exec, s[44:45]
	s_waitcnt lgkmcnt(0)
	s_barrier
	ds_read2st64_b32 v[18:19], v162 offset1:2
	v_lshlrev_b32_e32 v0, 6, v108
	v_lshlrev_b32_e32 v98, 2, v0
	v_lshl_add_u64 v[0:1], v[102:103], 0, v[98:99]
	global_load_dwordx4 v[24:27], v[0:1], off
	global_load_dwordx4 v[28:31], v[0:1], off offset:32
	global_load_dwordx4 v[32:35], v[0:1], off offset:64
	global_load_dwordx4 v[36:39], v[0:1], off offset:96
	s_add_i32 s61, s61, s88
	s_waitcnt lgkmcnt(0)
	v_add_f32_e32 v18, 0, v18
	v_add_f32_e32 v20, v18, v19
	ds_read2st64_b32 v[18:19], v162 offset0:4 offset1:6
	s_cmpk_lt_i32 s61, 0x100
	s_waitcnt lgkmcnt(0)
	v_add_f32_e32 v18, v20, v18
	v_add_f32_e32 v20, v18, v19
	ds_read2st64_b32 v[18:19], v162 offset0:8 offset1:10
	s_waitcnt lgkmcnt(0)
	v_add_f32_e32 v18, v20, v18
	v_add_f32_e32 v20, v18, v19
	ds_read2st64_b32 v[18:19], v162 offset0:12 offset1:14
	s_waitcnt lgkmcnt(0)
	v_add_f32_e32 v18, v20, v18
	v_add_f32_e32 v18, v18, v19
	v_fmamk_f32 v18, v18, 0x3b800000, v193
	v_cmp_gt_f32_e32 vcc, s60, v18
	v_mul_f32_e32 v19, 0x4b800000, v18
	s_nop 0
	v_cndmask_b32_e32 v18, v18, v19, vcc
	v_rsq_f32_e32 v18, v18
	s_nop 0
	v_mul_f32_e32 v19, 0x45800000, v18
	v_cndmask_b32_e32 v22, v18, v19, vcc
	s_waitcnt vmcnt(0)
	v_mov_b32_e32 v18, v24
	v_mov_b32_e32 v19, v25
	v_mov_b32_e32 v20, v26
	v_mov_b32_e32 v21, v27
	v_mul_f32_e32 v23, v107, v22
	v_mul_f32_e32 v18, v18, v23
	v_mul_f32_e32 v23, v105, v22
	v_mul_f32_e32 v19, v19, v23
	v_cvt_pk_bf16_f32 v18, v18, v19
	v_mul_f32_e32 v19, v208, v22
	v_mul_f32_e32 v19, v20, v19
	v_mul_f32_e32 v20, v209, v22
	v_mul_f32_e32 v20, v21, v20
	v_cvt_pk_bf16_f32 v19, v19, v20
	global_store_dwordx2 v[116:117], v[18:19], off offset:2048 sc0 sc1
	v_mov_b32_e32 v18, v28
	v_mov_b32_e32 v19, v29
	v_mov_b32_e32 v20, v30
	v_mov_b32_e32 v21, v31
	v_mul_f32_e32 v23, v210, v22
	v_mul_f32_e32 v18, v18, v23
	v_mul_f32_e32 v23, v211, v22
	v_mul_f32_e32 v19, v19, v23
	v_cvt_pk_bf16_f32 v18, v18, v19
	v_mul_f32_e32 v19, v212, v22
	v_mul_f32_e32 v19, v20, v19
	v_mul_f32_e32 v20, v213, v22
	v_mul_f32_e32 v20, v21, v20
	v_cvt_pk_bf16_f32 v19, v19, v20
	global_store_dwordx2 v[116:117], v[18:19], off offset:2064 sc0 sc1
	v_mov_b32_e32 v18, v32
	v_mov_b32_e32 v19, v33
	v_mov_b32_e32 v20, v34
	v_mov_b32_e32 v21, v35
	v_mul_f32_e32 v23, v214, v22
	v_mul_f32_e32 v18, v23, v18
	v_mul_f32_e32 v23, v215, v22
	v_mul_f32_e32 v19, v23, v19
	v_cvt_pk_bf16_f32 v18, v18, v19
	v_mul_f32_e32 v19, v216, v22
	v_mul_f32_e32 v19, v19, v20
	v_mul_f32_e32 v20, v217, v22
	v_mul_f32_e32 v20, v20, v21
	v_cvt_pk_bf16_f32 v19, v19, v20
	global_store_dwordx2 v[116:117], v[18:19], off offset:2080 sc0 sc1
	v_mov_b32_e32 v18, v36
	v_mov_b32_e32 v19, v37
	v_mov_b32_e32 v20, v38
	v_mov_b32_e32 v21, v39
	v_mul_f32_e32 v23, v218, v22
	v_mul_f32_e32 v18, v23, v18
	v_mul_f32_e32 v23, v219, v22
	v_mul_f32_e32 v19, v23, v19
	v_cvt_pk_bf16_f32 v18, v18, v19
	v_mul_f32_e32 v19, v220, v22
	v_mul_f32_e32 v19, v19, v20
	v_mul_f32_e32 v20, v221, v22
	v_mul_f32_e32 v20, v20, v21
	v_cvt_pk_bf16_f32 v19, v19, v20
	global_store_dwordx2 v[116:117], v[18:19], off offset:2096 sc0 sc1
	ds_read2st64_b32 v[18:19], v167 offset1:2
	s_waitcnt lgkmcnt(0)
	v_add_f32_e32 v18, 0, v18
	v_add_f32_e32 v20, v18, v19
	ds_read2st64_b32 v[18:19], v167 offset0:4 offset1:6
	s_waitcnt lgkmcnt(0)
	v_add_f32_e32 v18, v20, v18
	v_add_f32_e32 v20, v18, v19
	ds_read2st64_b32 v[18:19], v167 offset0:8 offset1:10
	s_waitcnt lgkmcnt(0)
	v_add_f32_e32 v18, v20, v18
	v_add_f32_e32 v20, v18, v19
	ds_read2st64_b32 v[18:19], v167 offset0:12 offset1:14
	s_waitcnt lgkmcnt(0)
	v_add_f32_e32 v18, v20, v18
	v_add_f32_e32 v18, v18, v19
	v_fmamk_f32 v18, v18, 0x3b800000, v193
	v_cmp_gt_f32_e32 vcc, s60, v18
	v_mul_f32_e32 v19, 0x4b800000, v18
	s_nop 0
	v_cndmask_b32_e32 v18, v18, v19, vcc
	v_rsq_f32_e32 v18, v18
	s_nop 0
	v_mul_f32_e32 v19, 0x45800000, v18
	v_cndmask_b32_e32 v22, v18, v19, vcc
	v_mov_b32_e32 v18, v24
	v_mov_b32_e32 v19, v25
	v_mov_b32_e32 v20, v26
	v_mov_b32_e32 v21, v27
	v_mul_f32_e32 v23, v140, v22
	v_mul_f32_e32 v18, v18, v23
	v_mul_f32_e32 v23, v141, v22
	v_mul_f32_e32 v19, v19, v23
	v_cvt_pk_bf16_f32 v18, v18, v19
	v_mul_f32_e32 v19, v222, v22
	v_mul_f32_e32 v19, v20, v19
	v_mul_f32_e32 v20, v223, v22
	v_mul_f32_e32 v20, v21, v20
	v_cvt_pk_bf16_f32 v19, v19, v20
	global_store_dwordx2 v[114:115], v[18:19], off offset:2048 sc0 sc1
	v_mov_b32_e32 v18, v28
	v_mov_b32_e32 v19, v29
	v_mov_b32_e32 v20, v30
	v_mov_b32_e32 v21, v31
	v_mul_f32_e32 v23, v138, v22
	v_mul_f32_e32 v18, v18, v23
	v_mul_f32_e32 v23, v139, v22
	v_mul_f32_e32 v19, v19, v23
	v_cvt_pk_bf16_f32 v18, v18, v19
	v_mul_f32_e32 v19, v225, v22
	v_mul_f32_e32 v19, v20, v19
	v_mul_f32_e32 v20, v226, v22
	v_mul_f32_e32 v20, v21, v20
	v_cvt_pk_bf16_f32 v19, v19, v20
	global_store_dwordx2 v[114:115], v[18:19], off offset:2064 sc0 sc1
	v_mov_b32_e32 v18, v32
	v_mov_b32_e32 v19, v33
	v_mov_b32_e32 v20, v34
	v_mov_b32_e32 v21, v35
	v_mul_f32_e32 v23, v136, v22
	v_mul_f32_e32 v18, v23, v18
	v_mul_f32_e32 v23, v137, v22
	v_mul_f32_e32 v19, v23, v19
	v_cvt_pk_bf16_f32 v18, v18, v19
	v_mul_f32_e32 v19, v227, v22
	v_mul_f32_e32 v19, v19, v20
	v_mul_f32_e32 v20, v228, v22
	v_mul_f32_e32 v20, v20, v21
	v_cvt_pk_bf16_f32 v19, v19, v20
	global_store_dwordx2 v[114:115], v[18:19], off offset:2080 sc0 sc1
	v_mov_b32_e32 v18, v36
	v_mov_b32_e32 v19, v37
	v_mov_b32_e32 v20, v38
	v_mov_b32_e32 v21, v39
	v_mul_f32_e32 v23, v134, v22
	v_mul_f32_e32 v18, v23, v18
	v_mul_f32_e32 v23, v135, v22
	v_mul_f32_e32 v19, v23, v19
	v_cvt_pk_bf16_f32 v18, v18, v19
	v_mul_f32_e32 v19, v229, v22
	v_mul_f32_e32 v19, v19, v20
	v_mul_f32_e32 v20, v230, v22
	v_mul_f32_e32 v20, v20, v21
	v_cvt_pk_bf16_f32 v19, v19, v20
	global_store_dwordx2 v[114:115], v[18:19], off offset:2096 sc0 sc1
	ds_read2st64_b32 v[18:19], v168 offset1:2
	s_waitcnt lgkmcnt(0)
	v_add_f32_e32 v18, 0, v18
	v_add_f32_e32 v20, v18, v19
	ds_read2st64_b32 v[18:19], v168 offset0:4 offset1:6
	s_waitcnt lgkmcnt(0)
	v_add_f32_e32 v18, v20, v18
	v_add_f32_e32 v20, v18, v19
	ds_read2st64_b32 v[18:19], v168 offset0:8 offset1:10
	s_waitcnt lgkmcnt(0)
	v_add_f32_e32 v18, v20, v18
	v_add_f32_e32 v20, v18, v19
	ds_read2st64_b32 v[18:19], v168 offset0:12 offset1:14
	s_waitcnt lgkmcnt(0)
	v_add_f32_e32 v18, v20, v18
	v_add_f32_e32 v18, v18, v19
	v_fmamk_f32 v18, v18, 0x3b800000, v193
	v_cmp_gt_f32_e32 vcc, s60, v18
	v_mul_f32_e32 v19, 0x4b800000, v18
	s_nop 0
	v_cndmask_b32_e32 v18, v18, v19, vcc
	v_rsq_f32_e32 v18, v18
	s_nop 0
	v_mul_f32_e32 v19, 0x45800000, v18
	v_cndmask_b32_e32 v22, v18, v19, vcc
	v_mov_b32_e32 v18, v24
	v_mov_b32_e32 v19, v25
	v_mov_b32_e32 v20, v26
	v_mov_b32_e32 v21, v27
	v_mul_f32_e32 v23, v132, v22
	v_mul_f32_e32 v18, v18, v23
	v_mul_f32_e32 v23, v133, v22
	v_mul_f32_e32 v19, v19, v23
	v_cvt_pk_bf16_f32 v18, v18, v19
	v_mul_f32_e32 v19, v232, v22
	v_mul_f32_e32 v19, v20, v19
	v_mul_f32_e32 v20, v233, v22
	v_mul_f32_e32 v20, v21, v20
	v_cvt_pk_bf16_f32 v19, v19, v20
	global_store_dwordx2 v[112:113], v[18:19], off offset:2048 sc0 sc1
	v_mov_b32_e32 v18, v28
	v_mov_b32_e32 v19, v29
	v_mov_b32_e32 v20, v30
	v_mov_b32_e32 v21, v31
	v_mul_f32_e32 v23, v130, v22
	v_mul_f32_e32 v18, v18, v23
	v_mul_f32_e32 v23, v131, v22
	v_mul_f32_e32 v19, v19, v23
	v_cvt_pk_bf16_f32 v18, v18, v19
	v_mul_f32_e32 v19, v234, v22
	v_mul_f32_e32 v19, v20, v19
	v_mul_f32_e32 v20, v235, v22
	v_mul_f32_e32 v20, v21, v20
	v_cvt_pk_bf16_f32 v19, v19, v20
	global_store_dwordx2 v[112:113], v[18:19], off offset:2064 sc0 sc1
	v_mov_b32_e32 v18, v32
	v_mov_b32_e32 v19, v33
	v_mov_b32_e32 v20, v34
	v_mov_b32_e32 v21, v35
	v_mul_f32_e32 v23, v128, v22
	v_mul_f32_e32 v18, v23, v18
	v_mul_f32_e32 v23, v129, v22
	v_mul_f32_e32 v19, v23, v19
	v_cvt_pk_bf16_f32 v18, v18, v19
	v_mul_f32_e32 v19, v236, v22
	v_mul_f32_e32 v19, v19, v20
	v_mul_f32_e32 v20, v237, v22
	v_mul_f32_e32 v20, v20, v21
	v_cvt_pk_bf16_f32 v19, v19, v20
	global_store_dwordx2 v[112:113], v[18:19], off offset:2080 sc0 sc1
	v_mov_b32_e32 v18, v36
	v_mov_b32_e32 v19, v37
	v_mov_b32_e32 v20, v38
	v_mov_b32_e32 v21, v39
	v_mul_f32_e32 v23, v126, v22
	v_mul_f32_e32 v18, v23, v18
	v_mul_f32_e32 v23, v127, v22
	v_mul_f32_e32 v19, v23, v19
	v_cvt_pk_bf16_f32 v18, v18, v19
	v_mul_f32_e32 v19, v238, v22
	v_mul_f32_e32 v19, v19, v20
	v_mul_f32_e32 v20, v239, v22
	v_mul_f32_e32 v20, v20, v21
	v_cvt_pk_bf16_f32 v19, v19, v20
	global_store_dwordx2 v[112:113], v[18:19], off offset:2096 sc0 sc1
	ds_read2st64_b32 v[18:19], v169 offset1:2
	s_waitcnt lgkmcnt(0)
	v_add_f32_e32 v18, 0, v18
	v_add_f32_e32 v20, v18, v19
	ds_read2st64_b32 v[18:19], v169 offset0:4 offset1:6
	s_waitcnt lgkmcnt(0)
	v_add_f32_e32 v18, v20, v18
	v_add_f32_e32 v20, v18, v19
	ds_read2st64_b32 v[18:19], v169 offset0:8 offset1:10
	s_waitcnt lgkmcnt(0)
	v_add_f32_e32 v18, v20, v18
	v_add_f32_e32 v20, v18, v19
	ds_read2st64_b32 v[18:19], v169 offset0:12 offset1:14
	s_waitcnt lgkmcnt(0)
	v_add_f32_e32 v18, v20, v18
	v_add_f32_e32 v18, v18, v19
	v_fmamk_f32 v18, v18, 0x3b800000, v193
	v_cmp_gt_f32_e32 vcc, s60, v18
	v_mul_f32_e32 v19, 0x4b800000, v18
	s_nop 0
	v_cndmask_b32_e32 v18, v18, v19, vcc
	v_rsq_f32_e32 v18, v18
	s_nop 0
	v_mul_f32_e32 v19, 0x45800000, v18
	v_cndmask_b32_e32 v22, v18, v19, vcc
	v_mov_b32_e32 v18, v24
	v_mov_b32_e32 v19, v25
	v_mov_b32_e32 v20, v26
	v_mov_b32_e32 v21, v27
	v_mul_f32_e32 v16, v16, v22
	v_mul_f32_e32 v17, v17, v22
	v_mul_f32_e32 v2, v2, v22
	v_mul_f32_e32 v3, v3, v22
	v_mul_f32_e32 v16, v18, v16
	v_mul_f32_e32 v17, v19, v17
	v_cvt_pk_bf16_f32 v16, v16, v17
	v_mul_f32_e32 v2, v20, v2
	v_mul_f32_e32 v3, v21, v3
	v_cvt_pk_bf16_f32 v17, v2, v3
	global_store_dwordx2 v[110:111], v[16:17], off offset:2048 sc0 sc1
	v_mov_b32_e32 v16, v28
	v_mov_b32_e32 v17, v29
	v_mov_b32_e32 v18, v30
	v_mov_b32_e32 v19, v31
	v_mul_f32_e32 v2, v4, v22
	v_mul_f32_e32 v3, v5, v22
	v_mul_f32_e32 v4, v7, v22
	v_mul_f32_e32 v2, v16, v2
	v_mul_f32_e32 v3, v17, v3
	v_cvt_pk_bf16_f32 v2, v2, v3
	v_mul_f32_e32 v3, v6, v22
	v_mul_f32_e32 v3, v18, v3
	v_mul_f32_e32 v4, v19, v4
	v_cvt_pk_bf16_f32 v3, v3, v4
	global_store_dwordx2 v[110:111], v[2:3], off offset:2064 sc0 sc1
	v_mov_b32_e32 v2, v32
	v_mov_b32_e32 v3, v33
	v_mov_b32_e32 v4, v34
	v_mov_b32_e32 v5, v35
	v_mul_f32_e32 v6, v8, v22
	v_mul_f32_e32 v2, v6, v2
	v_mul_f32_e32 v6, v9, v22
	v_mul_f32_e32 v3, v6, v3
	v_cvt_pk_bf16_f32 v2, v2, v3
	v_mul_f32_e32 v3, v10, v22
	v_mul_f32_e32 v3, v3, v4
	v_mul_f32_e32 v4, v11, v22
	v_mul_f32_e32 v4, v4, v5
	v_cvt_pk_bf16_f32 v3, v3, v4
	global_store_dwordx2 v[110:111], v[2:3], off offset:2080 sc0 sc1
	v_mov_b32_e32 v0, v36
	v_mov_b32_e32 v1, v37
	v_mov_b32_e32 v2, v38
	v_mov_b32_e32 v3, v39
	v_mul_f32_e32 v4, v12, v22
	v_mul_f32_e32 v0, v4, v0
	v_mul_f32_e32 v4, v13, v22
	v_mul_f32_e32 v1, v4, v1
	v_cvt_pk_bf16_f32 v0, v0, v1
	v_mul_f32_e32 v1, v14, v22
	v_mul_f32_e32 v1, v1, v2
	v_mul_f32_e32 v2, v15, v22
	v_mul_f32_e32 v2, v2, v3
	v_cvt_pk_bf16_f32 v1, v1, v2
	global_store_dwordx2 v[110:111], v[0:1], off offset:2096 sc0 sc1
	v_mov_b32_e32 v0, v159
	s_cbranch_scc0 .LBB0_1000

.Lmy_cmb_loop:
	v_lshl_add_u64 v[176:177], s[84:85], 0, v[10:11]
	v_add_co_u32_e64 v190, s[0:1], s5, v176
	v_lshl_add_u64 v[174:175], s[84:85], 0, v[12:13]
	s_nop 0
	v_addc_co_u32_e64 v191, s[0:1], 0, v177, s[0:1]
	v_add_co_u32_e64 v214, s[0:1], s20, v176
	v_lshl_add_u64 v[188:189], s[84:85], 0, v[8:9]
	s_nop 0
	v_addc_co_u32_e64 v215, s[0:1], 0, v177, s[0:1]
	v_add_co_u32_e64 v218, s[0:1], s21, v176
	v_add_co_u32_e32 v208, vcc, 0x5100000, v174
	s_nop 0
	v_addc_co_u32_e64 v219, s[0:1], 0, v177, s[0:1]
	v_lshl_add_u64 v[212:213], v[176:177], 0, s[14:15]
	v_lshl_add_u64 v[210:211], v[176:177], 0, s[16:17]
	v_lshl_add_u64 v[216:217], v[176:177], 0, s[18:19]
	v_add_co_u32_e64 v176, s[0:1], s23, v188
	v_addc_co_u32_e32 v209, vcc, 0, v175, vcc
	v_addc_co_u32_e64 v177, s[0:1], 0, v189, s[0:1]
	global_load_dwordx4 v[188:191], v[190:191], off
	s_nop 0
	global_load_dwordx4 v[192:195], v[214:215], off
	global_load_dwordx4 v[196:199], v[218:219], off
	global_load_dwordx4 v[200:203], v[210:211], off offset:16
	global_load_dwordx4 v[204:207], v[216:217], off offset:16
	v_add_co_u32_e32 v210, vcc, 0x5180000, v174
	global_load_dword v224, v[208:209], off
	s_nop 0
	v_addc_co_u32_e32 v211, vcc, 0, v175, vcc
	v_add_co_u32_e32 v174, vcc, 0x5200000, v174
	v_add_u32_e32 v164, s4, v4
	s_nop 0
	v_addc_co_u32_e32 v175, vcc, 0, v175, vcc
	global_load_dword v225, v[210:211], off
	global_load_dword v226, v[174:175], off
	s_nop 0
	global_load_dwordx4 v[208:211], v[212:213], off offset:16
	v_lshl_add_u64 v[168:169], v[8:9], 0, s[6:7]
	v_lshl_add_u64 v[170:171], v[10:11], 0, s[8:9]
	v_lshl_add_u64 v[172:173], v[12:13], 0, s[10:11]
	s_waitcnt vmcnt(17)
	v_mov_b32_e32 v0, v234
	v_mov_b32_e32 v1, v235
	v_mov_b32_e32 v2, v236
	v_mov_b32_e32 v3, v237
	v_mov_b32_e32 v24, v230
	v_mov_b32_e32 v25, v231
	v_mov_b32_e32 v26, v232
	v_mov_b32_e32 v27, v233
	v_lshlrev_b32_e32 v67, 16, v28
	v_and_b32_e32 v68, 0xffff0000, v28
	v_lshlrev_b32_e32 v69, 16, v29
	v_and_b32_e32 v70, 0xffff0000, v29
	v_lshlrev_b32_e32 v71, 16, v30
	v_and_b32_e32 v72, 0xffff0000, v30
	v_lshlrev_b32_e32 v73, 16, v31
	v_and_b32_e32 v74, 0xffff0000, v31
	s_waitcnt vmcnt(15)
	v_lshlrev_b32_e32 v14, 16, v39
	v_lshlrev_b32_e32 v29, 16, v32
	v_lshlrev_b32_e32 v28, 16, v36
	v_and_b32_e32 v31, 0xffff0000, v32
	v_and_b32_e32 v30, 0xffff0000, v36
	v_lshlrev_b32_e32 v52, 16, v37
	s_waitcnt vmcnt(10)
	v_max3_f32 v75, v64, v65, v66
	v_and_b32_e32 v32, 0xffff0000, v37
	v_lshlrev_b32_e32 v37, 16, v34
	v_lshlrev_b32_e32 v36, 16, v38
	v_and_b32_e32 v55, 0xffff0000, v34
	v_and_b32_e32 v54, 0xffff0000, v38
	v_and_b32_e32 v34, 0xffff0000, v39
	v_lshlrev_b32_e32 v39, 16, v40
	v_lshlrev_b32_e32 v38, 16, v44
	v_and_b32_e32 v57, 0xffff0000, v40
	v_and_b32_e32 v56, 0xffff0000, v44
	v_lshlrev_b32_e32 v58, 16, v45
	v_and_b32_e32 v40, 0xffff0000, v45
	v_lshlrev_b32_e32 v45, 16, v42
	v_lshlrev_b32_e32 v44, 16, v46
	v_and_b32_e32 v61, 0xffff0000, v42
	v_and_b32_e32 v60, 0xffff0000, v46
	v_lshlrev_b32_e32 v62, 16, v47
	v_and_b32_e32 v42, 0xffff0000, v47
	s_waitcnt vmcnt(9)
	v_lshlrev_b32_e32 v76, 16, v48
	v_and_b32_e32 v77, 0xffff0000, v48
	v_lshlrev_b32_e32 v78, 16, v49
	v_and_b32_e32 v79, 0xffff0000, v49
	v_and_b32_e32 v46, 0xffff0000, v50
	v_lshlrev_b32_e32 v47, 16, v50
	v_and_b32_e32 v48, 0xffff0000, v51
	v_lshlrev_b32_e32 v49, 16, v51
	v_sub_f32_e32 v50, v64, v75
	v_sub_f32_e32 v51, v65, v75
	v_sub_f32_e32 v64, v66, v75
	v_mul_f32_e32 v50, 0x3fb8aa3b, v50
	v_mul_f32_e32 v51, 0x3fb8aa3b, v51
	v_mul_f32_e32 v64, 0x3fb8aa3b, v64
	v_exp_f32_e32 v65, v50
	v_exp_f32_e32 v51, v51
	v_exp_f32_e32 v50, v64
	v_lshlrev_b32_e32 v59, 16, v41
	v_and_b32_e32 v41, 0xffff0000, v41
	v_add_f32_e32 v64, v65, v51
	v_add_f32_e32 v64, v50, v64
	v_div_scale_f32 v66, s[0:1], v64, v64, 1.0
	v_rcp_f32_e32 v80, v66
	v_div_scale_f32 v75, vcc, 1.0, v64, 1.0
	v_lshlrev_b32_e32 v63, 16, v43
	v_fma_f32 v81, -v66, v80, 1.0
	v_fmac_f32_e32 v80, v81, v80
	v_mul_f32_e32 v81, v75, v80
	v_fma_f32 v82, -v66, v81, v75
	v_fmac_f32_e32 v81, v82, v80
	v_fma_f32 v66, -v66, v81, v75
	v_div_fmas_f32 v66, v66, v80, v81
	v_div_fixup_f32 v64, v66, v64, 1.0
	v_mul_f32_e32 v66, v65, v64
	v_pk_mul_f32 v[50:51], v[50:51], v[64:65] op_sel_hi:[1,0]
	v_fma_f32 v65, v66, v68, 0
	v_pk_mul_f32 v[30:31], v[50:51], v[30:31]
	v_lshlrev_b32_e32 v15, 16, v35
	v_lshlrev_b32_e32 v53, 16, v33
	v_and_b32_e32 v33, 0xffff0000, v33
	v_and_b32_e32 v35, 0xffff0000, v35
	v_and_b32_e32 v43, 0xffff0000, v43
	v_fma_f32 v64, v66, v67, 0
	v_fma_f32 v67, v66, v69, 0
	v_fma_f32 v69, v66, v71, 0
	v_fma_f32 v71, v66, v73, 0
	v_fma_f32 v73, v66, v76, 0
	v_fma_f32 v76, v66, v79, 0
	v_pk_mul_f32 v[28:29], v[50:51], v[28:29]
	v_pk_mul_f32 v[40:41], v[50:51], v[40:41]
	v_pk_mul_f32 v[44:45], v[50:51], v[44:45]
	v_pk_mul_f32 v[62:63], v[50:51], v[62:63]
	v_add_f32_e32 v31, v31, v65
	v_pk_mul_f32 v[14:15], v[50:51], v[14:15]
	v_pk_mul_f32 v[52:53], v[50:51], v[52:53]
	v_pk_mul_f32 v[32:33], v[50:51], v[32:33]
	v_pk_mul_f32 v[36:37], v[50:51], v[36:37]
	v_pk_mul_f32 v[54:55], v[50:51], v[54:55]
	v_pk_mul_f32 v[34:35], v[50:51], v[34:35]
	v_pk_mul_f32 v[38:39], v[50:51], v[38:39]
	v_pk_mul_f32 v[56:57], v[50:51], v[56:57]
	v_pk_mul_f32 v[58:59], v[50:51], v[58:59]
	v_pk_mul_f32 v[60:61], v[50:51], v[60:61]
	v_pk_mul_f32 v[42:43], v[50:51], v[42:43]
	v_add_f32_e32 v29, v29, v64
	v_add_f32_e32 v41, v41, v76
	v_mov_b32_e32 v51, v45
	v_mov_b32_e32 v45, v63
	v_add_f32_e32 v63, v30, v31
	v_fma_f32 v68, v66, v70, 0
	v_add_f32_e32 v53, v53, v67
	v_mov_b32_e32 v50, v61
	v_mov_b32_e32 v61, v44
	v_mov_b32_e32 v44, v43
	v_mov_b32_e32 v43, v62
	v_add_f32_e32 v62, v28, v29
	v_add_f32_e32 v40, v40, v41
	v_mul_f32_e32 v41, v63, v63
	v_add_f32_e32 v33, v33, v68
	v_add_f32_e32 v52, v52, v53
	v_fmac_f32_e32 v41, v62, v62
	v_fma_f32 v70, v66, v72, 0
	v_add_f32_e32 v37, v37, v69
	v_add_f32_e32 v53, v32, v33
	v_fmac_f32_e32 v41, v52, v52
	v_add_f32_e32 v55, v55, v70
	v_add_f32_e32 v36, v36, v37
	v_fmac_f32_e32 v41, v53, v53
	v_fma_f32 v72, v66, v74, 0
	v_add_f32_e32 v15, v15, v71
	v_add_f32_e32 v37, v54, v55
	v_fmac_f32_e32 v41, v36, v36
	v_add_f32_e32 v35, v35, v72
	v_add_f32_e32 v54, v14, v15
	v_fmac_f32_e32 v41, v37, v37
	v_fma_f32 v74, v66, v77, 0
	v_add_f32_e32 v39, v39, v73
	v_add_f32_e32 v34, v34, v35
	v_fmac_f32_e32 v41, v54, v54
	v_fma_f32 v75, v66, v78, 0
	v_add_f32_e32 v57, v57, v74
	v_add_f32_e32 v35, v38, v39
	v_fmac_f32_e32 v41, v34, v34
	v_pk_fma_f32 v[46:47], v[66:67], v[46:47], 0 op_sel_hi:[0,1,0]
	v_add_f32_e32 v59, v59, v75
	v_add_f32_e32 v38, v56, v57
	v_fmac_f32_e32 v41, v35, v35
	v_add_f32_e32 v39, v58, v59
	v_pk_add_f32 v[14:15], v[50:51], v[46:47]
	v_fmac_f32_e32 v41, v38, v38
	v_pk_fma_f32 v[48:49], v[66:67], v[48:49], 0 op_sel_hi:[0,1,0]
	v_pk_add_f32 v[14:15], v[60:61], v[14:15]
	v_fmac_f32_e32 v41, v39, v39
	v_pk_add_f32 v[28:29], v[44:45], v[48:49]
	v_pk_mul_f32 v[30:31], v[14:15], v[14:15]
	v_fmac_f32_e32 v41, v40, v40
	v_pk_add_f32 v[28:29], v[42:43], v[28:29]
	v_add_f32_e32 v31, v31, v41
	v_pk_mul_f32 v[32:33], v[28:29], v[28:29]
	v_add_f32_e32 v30, v30, v31
	v_add_f32_e32 v30, v33, v30
	v_add_f32_e32 v30, v32, v30
	ds_bpermute_b32 v31, v18, v30
	s_waitcnt lgkmcnt(0)
	v_add_f32_e32 v30, v30, v31
	ds_bpermute_b32 v31, v19, v30
	s_waitcnt lgkmcnt(0)
	v_add_f32_e32 v30, v30, v31
	ds_bpermute_b32 v31, v20, v30
	s_waitcnt lgkmcnt(0)
	v_add_f32_e32 v30, v30, v31
	ds_bpermute_b32 v31, v21, v30
	s_waitcnt lgkmcnt(0)
	v_add_f32_e32 v30, v30, v31
	ds_bpermute_b32 v31, v22, v30
	s_waitcnt lgkmcnt(0)
	v_add_f32_e32 v30, v30, v31
	ds_bpermute_b32 v31, v23, v30
	s_waitcnt lgkmcnt(0)
	v_add_f32_e32 v30, v30, v31
	v_fmamk_f32 v30, v30, 0x3a800000, v5
	v_mul_f32_e32 v31, 0x4b800000, v30
	v_cmp_gt_f32_e32 vcc, s22, v30
	s_nop 1
	v_cndmask_b32_e32 v30, v30, v31, vcc
	v_rsq_f32_e32 v30, v30
	s_nop 0
	v_mul_f32_e32 v31, 0x45800000, v30
	v_cndmask_b32_e32 v30, v30, v31, vcc
	v_mul_f32_e32 v34, v34, v30
	v_mul_f32_e32 v31, v62, v30
	v_mul_f32_e32 v32, v63, v30
	v_mul_f32_e32 v33, v52, v30
	v_mul_f32_e32 v41, v53, v30
	v_mul_f32_e32 v36, v36, v30
	v_mul_f32_e32 v37, v37, v30
	v_mul_f32_e32 v42, v54, v30
	v_mul_f32_e32 v3, v3, v34
	v_mul_f32_e32 v24, v24, v31
	v_mul_f32_e32 v25, v25, v32
	v_mul_f32_e32 v26, v26, v33
	v_mul_f32_e32 v27, v27, v41
	v_mul_f32_e32 v31, v0, v36
	v_mul_f32_e32 v32, v1, v37
	v_mul_f32_e32 v33, v2, v42
	v_cvt_pk_bf16_f32 v0, v24, v25
	v_cvt_pk_bf16_f32 v1, v26, v27
	v_cvt_pk_bf16_f32 v2, v31, v32
	v_cvt_pk_bf16_f32 v3, v33, v3
	global_store_dwordx4 v[16:17], v[0:3], off sc0 sc1
	s_nop 1
	v_mov_b32_e32 v0, v238
	v_mov_b32_e32 v1, v239
	v_mov_b32_e32 v2, v240
	v_mov_b32_e32 v3, v241
	s_nop 0
	v_mov_b32_e32 v24, v242
	v_mov_b32_e32 v25, v243
	v_mov_b32_e32 v26, v244
	v_mov_b32_e32 v27, v245
	v_cmp_lt_i32_e32 vcc, s24, v4
	v_mul_f32_e32 v31, v35, v30
	v_mul_f32_e32 v32, v38, v30
	v_mul_f32_e32 v33, v39, v30
	v_mul_f32_e32 v34, v40, v30
	s_or_b64 s[12:13], vcc, s[12:13]
	v_mul_f32_e32 v15, v15, v30
	v_mul_f32_e32 v14, v14, v30
	v_mul_f32_e32 v29, v29, v30
	v_mul_f32_e32 v28, v28, v30
	v_mul_f32_e32 v0, v0, v31
	v_mul_f32_e32 v1, v1, v32
	v_mul_f32_e32 v2, v2, v33
	v_mul_f32_e32 v3, v3, v34
	v_mul_f32_e32 v15, v24, v15
	v_mul_f32_e32 v14, v25, v14
	v_mul_f32_e32 v24, v26, v29
	v_mul_f32_e32 v25, v27, v28
	v_cvt_pk_bf16_f32 v0, v0, v1
	v_cvt_pk_bf16_f32 v1, v2, v3
	v_cvt_pk_bf16_f32 v2, v15, v14
	v_cvt_pk_bf16_f32 v3, v24, v25
	global_store_dwordx4 v[16:17], v[0:3], off offset:16 sc0 sc1
	s_andn2_b64 exec, exec, s[12:13]
	s_cbranch_execz .Lmy_cmb_exit
	s_waitcnt vmcnt(2)
	v_mov_b32_e32 v4, v164
	v_mov_b32_e32 v8, v168
	v_mov_b32_e32 v9, v169
	v_mov_b32_e32 v10, v170
	v_mov_b32_e32 v11, v171
	v_mov_b32_e32 v12, v172
	v_mov_b32_e32 v13, v173
	v_mov_b32_e32 v14, v174
	v_mov_b32_e32 v15, v175
	v_mov_b32_e32 v16, v176
	v_mov_b32_e32 v17, v177
	v_mov_b32_e32 v28, v188
	v_mov_b32_e32 v29, v189
	v_mov_b32_e32 v30, v190
	v_mov_b32_e32 v31, v191
	v_mov_b32_e32 v32, v192
	v_mov_b32_e32 v33, v193
	v_mov_b32_e32 v34, v194
	v_mov_b32_e32 v35, v195
	v_mov_b32_e32 v36, v196
	v_mov_b32_e32 v37, v197
	v_mov_b32_e32 v38, v198
	v_mov_b32_e32 v39, v199
	v_mov_b32_e32 v40, v200
	v_mov_b32_e32 v41, v201
	v_mov_b32_e32 v42, v202
	v_mov_b32_e32 v43, v203
	v_mov_b32_e32 v44, v204
	v_mov_b32_e32 v45, v205
	v_mov_b32_e32 v46, v206
	v_mov_b32_e32 v47, v207
	v_mov_b32_e32 v48, v208
	v_mov_b32_e32 v49, v209
	v_mov_b32_e32 v50, v210
	v_mov_b32_e32 v51, v211
	v_mov_b32_e32 v52, v212
	v_mov_b32_e32 v53, v213
	v_mov_b32_e32 v54, v214
	v_mov_b32_e32 v55, v215
	v_mov_b32_e32 v56, v216
	v_mov_b32_e32 v57, v217
	v_mov_b32_e32 v58, v218
	v_mov_b32_e32 v59, v219
	v_mov_b32_e32 v64, v224
	v_mov_b32_e32 v65, v225
	v_mov_b32_e32 v66, v226
	s_branch .Lmy_cmb_loop

.Lmy_kv_loop:
	v_ashrrev_i32_e32 v22, 2, v10
	v_ashrrev_i32_e32 v23, 31, v22
	v_lshlrev_b64 v[26:27], 12, v[22:23]
	v_lshl_add_u64 v[24:25], v[22:23], 2, s[2:3]
	v_lshl_add_u64 v[26:27], v[6:7], 0, v[26:27]
	global_load_dword v28, v[24:25], off
	global_load_dwordx2 v[30:31], v[26:27], off
	global_load_dwordx2 v[32:33], v[26:27], off offset:2048
	v_add_co_u32_e32 v24, vcc, 0x400000, v26
	v_ashrrev_i32_e32 v0, 8, v10
	s_nop 0
	v_addc_co_u32_e32 v25, vcc, 0, v27, vcc
	global_load_dwordx2 v[26:27], v[24:25], off
	global_load_dwordx2 v[34:35], v[24:25], off offset:2048
	global_load_dwordx2 v[36:37], v[2:3], off
	v_and_or_b32 v24, v0, -4, v17
	v_ashrrev_i32_e32 v25, 31, v24
	v_lshlrev_b64 v[24:25], 16, v[24:25]
	v_lshlrev_b32_sdwa v0, v19, v22 dst_sel:DWORD dst_unused:UNUSED_PAD src0_sel:DWORD src1_sel:BYTE_0
	v_lshl_add_u64 v[38:39], s[4:5], 0, v[24:25]
	v_lshl_add_u64 v[24:25], v[4:5], 0, v[24:25]
	v_lshl_add_u64 v[38:39], v[38:39], 0, v[0:1]
	v_lshlrev_b32_sdwa v0, v20, v22 dst_sel:DWORD dst_unused:UNUSED_PAD src0_sel:DWORD src1_sel:BYTE_0
	v_lshl_add_u64 v[24:25], v[24:25], 0, v[0:1]
	v_add_u32_e32 v10, s8, v10
	v_cmp_lt_i32_e32 vcc, s11, v10
	s_or_b64 s[6:7], vcc, s[6:7]
	v_lshl_add_u64 v[22:23], v[38:39], 0, v[8:9]
	s_waitcnt vmcnt(0)
	v_pk_add_f32 v[30:31], v[30:31], 0 op_sel_hi:[1,0]
	v_add_f32_e32 v0, 0, v32
	v_add_f32_e32 v21, 0, v33
	v_pk_add_f32 v[26:27], v[30:31], v[26:27]
	v_add_f32_e32 v0, v0, v34
	v_add_f32_e32 v21, v21, v35
	v_pk_mul_f32 v[26:27], v[28:29], v[26:27] op_sel_hi:[0,1]
	v_mul_f32_e32 v0, v28, v0
	v_mul_f32_e32 v21, v28, v21
	v_pk_mul_f32 v[28:29], v[26:27], v[26:27]
	v_bfe_u32 v30, v0, 16, 1
	v_add_f32_e32 v28, v29, v28
	ds_bpermute_b32 v29, v11, v28
	v_bfe_u32 v31, v21, 16, 1
	v_add3_u32 v0, v0, v30, s10
	v_add3_u32 v21, v21, v31, s10
	s_waitcnt lgkmcnt(0)
	v_add_f32_e32 v28, v28, v29
	ds_bpermute_b32 v29, v12, v28
	s_waitcnt lgkmcnt(0)
	v_add_f32_e32 v28, v28, v29
	ds_bpermute_b32 v29, v13, v28
	s_waitcnt lgkmcnt(0)
	v_add_f32_e32 v28, v28, v29
	ds_bpermute_b32 v29, v14, v28
	s_waitcnt lgkmcnt(0)
	v_add_f32_e32 v28, v28, v29
	ds_bpermute_b32 v29, v15, v28
	s_waitcnt lgkmcnt(0)
	v_add_f32_e32 v28, v28, v29
	ds_bpermute_b32 v29, v16, v28
	s_waitcnt lgkmcnt(0)
	v_add_f32_e32 v28, v28, v29
	v_fmamk_f32 v28, v28, 0x3c000000, v18
	v_mul_f32_e32 v29, 0x4b800000, v28
	v_cmp_gt_f32_e32 vcc, s9, v28
	s_nop 1
	v_cndmask_b32_e32 v28, v28, v29, vcc
	v_rsq_f32_e32 v28, v28
	s_nop 0
	v_mul_f32_e32 v29, 0x45800000, v28
	v_cndmask_b32_e32 v28, v28, v29, vcc
	v_mul_f32_e32 v26, v26, v28
	v_mul_f32_e32 v27, v27, v28
	v_mul_f32_e32 v26, v36, v26
	v_mul_f32_e32 v27, v37, v27
	v_cvt_pk_bf16_f32 v26, v26, v27
	global_store_short_d16_hi v[24:25], v0, off sc0 sc1
	global_store_short_d16_hi v[24:25], v21, off offset:512 sc0 sc1
	global_store_dword v[22:23], v26, off sc0 sc1
	s_andn2_b64 exec, exec, s[6:7]
	s_cbranch_execnz .Lmy_kv_loop

.LBB0_1179:
	v_lshl_or_b32 v144, s23, 8, v148
	s_ashr_i32 s23, s22, 31
	s_lshl_b64 s[22:23], s[22:23], 23
	s_add_u32 s22, s48, s22
	v_lshl_add_u32 v152, s28, 8, v146
	s_addc_u32 s23, s49, s23
	v_ashrrev_i32_e32 v145, 31, v144
	v_ashrrev_i32_e32 v153, 31, v152
	v_lshl_add_u64 v[154:155], v[144:145], 1, s[22:23]
	v_lshlrev_b64 v[144:145], 10, v[152:153]
	v_lshl_add_u64 v[144:145], v[154:155], 0, v[144:145]
	v_cvt_pk_bf16_f32 v124, v124, v125
	v_cvt_pk_bf16_f32 v125, v126, v127
	v_cvt_pk_bf16_f32 v126, v120, v121
	v_cvt_pk_bf16_f32 v127, v122, v123
	global_store_dwordx4 v[144:145], v[124:127], off sc0 sc1
	v_cvt_pk_bf16_f32 v112, v112, v113
	v_cvt_pk_bf16_f32 v113, v114, v115
	v_cvt_pk_bf16_f32 v114, v104, v105
	v_or_b32_e32 v104, 16, v152
	v_ashrrev_i32_e32 v105, 31, v104
	v_lshlrev_b64 v[104:105], 10, v[104:105]
	v_cvt_pk_bf16_f32 v115, v106, v107
	global_store_dwordx4 v[144:145], v[112:115], off offset:256 sc0 sc1
	s_nop 1
	v_lshl_add_u64 v[112:113], v[154:155], 0, v[104:105]
	v_cvt_pk_bf16_f32 v104, v116, v117
	v_cvt_pk_bf16_f32 v105, v118, v119
	v_cvt_pk_bf16_f32 v106, v108, v109
	v_cvt_pk_bf16_f32 v107, v110, v111
	global_store_dwordx4 v[112:113], v[104:107], off sc0 sc1
	v_cvt_pk_bf16_f32 v96, v96, v97
	v_cvt_pk_bf16_f32 v97, v98, v99
	v_cvt_pk_bf16_f32 v98, v88, v89
	v_or_b32_e32 v88, 32, v152
	v_ashrrev_i32_e32 v89, 31, v88
	v_lshlrev_b64 v[88:89], 10, v[88:89]
	v_cvt_pk_bf16_f32 v99, v90, v91
	global_store_dwordx4 v[112:113], v[96:99], off offset:256 sc0 sc1
	s_nop 1
	v_lshl_add_u64 v[96:97], v[154:155], 0, v[88:89]
	v_cvt_pk_bf16_f32 v88, v100, v101
	v_cvt_pk_bf16_f32 v89, v102, v103
	v_cvt_pk_bf16_f32 v90, v92, v93
	v_cvt_pk_bf16_f32 v91, v94, v95
	global_store_dwordx4 v[96:97], v[88:91], off sc0 sc1
	v_cvt_pk_bf16_f32 v80, v80, v81
	v_cvt_pk_bf16_f32 v81, v82, v83
	v_cvt_pk_bf16_f32 v82, v72, v73
	v_or_b32_e32 v72, 48, v152
	v_ashrrev_i32_e32 v73, 31, v72
	v_lshlrev_b64 v[72:73], 10, v[72:73]
	v_cvt_pk_bf16_f32 v83, v74, v75
	global_store_dwordx4 v[96:97], v[80:83], off offset:256 sc0 sc1
	s_nop 1
	v_lshl_add_u64 v[80:81], v[154:155], 0, v[72:73]
	v_cvt_pk_bf16_f32 v72, v84, v85
	v_cvt_pk_bf16_f32 v73, v86, v87
	v_cvt_pk_bf16_f32 v74, v76, v77
	v_cvt_pk_bf16_f32 v75, v78, v79
	global_store_dwordx4 v[80:81], v[72:75], off sc0 sc1
	v_cvt_pk_bf16_f32 v68, v68, v69
	v_cvt_pk_bf16_f32 v69, v70, v71
	v_cvt_pk_bf16_f32 v70, v64, v65
	v_cvt_pk_bf16_f32 v71, v66, v67
	global_store_dwordx4 v[80:81], v[68:71], off offset:256 sc0 sc1
	v_cvt_pk_bf16_f32 v60, v60, v61
	v_cvt_pk_bf16_f32 v61, v62, v63
	v_cvt_pk_bf16_f32 v62, v56, v57
	v_add_co_u32_e32 v56, vcc, s55, v144
	v_lshl_add_u64 v[64:65], v[144:145], 0, s[8:9]
	s_nop 0
	v_addc_co_u32_e32 v57, vcc, 0, v145, vcc
	v_cvt_pk_bf16_f32 v63, v58, v59
	global_store_dwordx4 v[56:57], v[60:63], off sc0 sc1
	v_cvt_pk_bf16_f32 v48, v48, v49
	v_cvt_pk_bf16_f32 v49, v50, v51
	v_cvt_pk_bf16_f32 v50, v40, v41
	v_cvt_pk_bf16_f32 v51, v42, v43
	global_store_dwordx4 v[64:65], v[48:51], off offset:256 sc0 sc1
	v_cvt_pk_bf16_f32 v40, v52, v53
	v_cvt_pk_bf16_f32 v41, v54, v55
	v_cvt_pk_bf16_f32 v42, v44, v45
	v_add_co_u32_e32 v44, vcc, s56, v144
	s_nop 0
	v_lshl_add_u64 v[48:49], v[144:145], 0, s[10:11]
	v_addc_co_u32_e32 v45, vcc, 0, v145, vcc
	v_cvt_pk_bf16_f32 v43, v46, v47
	global_store_dwordx4 v[44:45], v[40:43], off sc0 sc1
	v_cvt_pk_bf16_f32 v32, v32, v33
	v_cvt_pk_bf16_f32 v33, v34, v35
	v_cvt_pk_bf16_f32 v34, v24, v25
	v_cvt_pk_bf16_f32 v35, v26, v27
	global_store_dwordx4 v[48:49], v[32:35], off offset:256 sc0 sc1
	v_cvt_pk_bf16_f32 v24, v36, v37
	v_cvt_pk_bf16_f32 v25, v38, v39
	v_cvt_pk_bf16_f32 v26, v28, v29
	v_add_co_u32_e32 v28, vcc, s57, v144
	s_nop 0
	v_lshl_add_u64 v[32:33], v[144:145], 0, s[12:13]
	v_addc_co_u32_e32 v29, vcc, 0, v145, vcc
	v_cvt_pk_bf16_f32 v27, v30, v31
	global_store_dwordx4 v[28:29], v[24:27], off sc0 sc1
	v_cvt_pk_bf16_f32 v16, v16, v17
	v_cvt_pk_bf16_f32 v17, v18, v19
	v_cvt_pk_bf16_f32 v18, v8, v9
	v_cvt_pk_bf16_f32 v19, v10, v11
	global_store_dwordx4 v[32:33], v[16:19], off offset:256 sc0 sc1
	v_cvt_pk_bf16_f32 v8, v20, v21
	v_cvt_pk_bf16_f32 v9, v22, v23
	v_cvt_pk_bf16_f32 v10, v12, v13
	v_add_co_u32_e32 v12, vcc, s58, v144
	s_nop 0
	v_lshl_add_u64 v[16:17], v[144:145], 0, s[14:15]
	v_addc_co_u32_e32 v13, vcc, 0, v145, vcc
	s_andn2_b64 vcc, exec, s[0:1]
	s_mov_b64 s[0:1], -1
	v_cvt_pk_bf16_f32 v11, v14, v15
	global_store_dwordx4 v[12:13], v[8:11], off sc0 sc1
	v_cvt_pk_bf16_f32 v4, v4, v5
	v_cvt_pk_bf16_f32 v5, v6, v7
	v_cvt_pk_bf16_f32 v6, v0, v1
	v_cvt_pk_bf16_f32 v7, v2, v3
	global_store_dwordx4 v[16:17], v[4:7], off offset:256 sc0 sc1
	s_cbranch_vccnz .LBB0_1168
	s_andn2_b64 vcc, exec, s[2:3]
	s_cbranch_vccnz .LBB0_1167
	s_barrier
	s_branch .LBB0_1167

.LBB0_1244:
	v_add_u32_e32 v129, 0, v112
	ds_read_b128 v[64:67], v129
	ds_read_b128 v[182:185], v129 offset:32
	v_add_u32_e32 v131, 0, v123
	v_add_u32_e32 v139, 0x15200, v131
	v_add_u32_e32 v133, 0x11010, v131
	s_waitcnt lgkmcnt(1)
	v_mfma_f32_32x32x16_bf16 v[64:79], v[64:67], v[80:83], 0
	v_add_u32_e32 v135, 0x11020, v131
	v_add_u32_e32 v137, 0x11030, v131
	v_add_u32_e32 v141, 0x15210, v131
	v_add_u32_e32 v143, 0x15220, v131
	v_add_u32_e32 v145, 0x15230, v131
	v_add_u32_e32 v195, 0x1d620, v131
	v_add_u32_e32 v147, 0x19400, v131
	s_waitcnt lgkmcnt(0)
	v_mfma_f32_32x32x16_bf16 v[64:79], v[182:185], v[84:87], v[64:79]
	ds_read_b128 v[182:185], v129 offset:64
	ds_read_b128 v[186:189], v129 offset:96
	v_add_u32_e32 v151, 0x19420, v131
	v_add_u32_e32 v155, 0x1d600, v131
	v_add_u32_e32 v149, 0x19410, v131
	v_add_u32_e32 v153, 0x19430, v131
	v_add_u32_e32 v181, 0x1d610, v131
	s_add_i32 s11, s11, -1
	s_waitcnt lgkmcnt(1)
	v_mfma_f32_32x32x16_bf16 v[64:79], v[182:185], v[88:91], v[64:79]
	v_add_u32_e32 v123, 64, v123
	v_add_u32_e32 v112, 0x2200, v112
	s_cmp_lg_u32 s11, 0
	s_waitcnt lgkmcnt(0)
	v_mfma_f32_32x32x16_bf16 v[64:79], v[186:189], v[92:95], v[64:79]
	ds_read_b128 v[182:185], v129 offset:128
	ds_read_b128 v[186:189], v129 offset:160
	s_waitcnt lgkmcnt(1)
	v_mfma_f32_32x32x16_bf16 v[64:79], v[182:185], v[96:99], v[64:79]
	ds_read_b128 v[182:185], v129 offset:192
	ds_read_b128 v[190:193], v129 offset:224
	v_add_u32_e32 v129, 0x11000, v131
	v_add_u32_e32 v131, 0x1d630, v131
	s_waitcnt lgkmcnt(2)
	v_mfma_f32_32x32x16_bf16 v[64:79], v[186:189], v[100:103], v[64:79]
	s_waitcnt lgkmcnt(1)
	v_mfma_f32_32x32x16_bf16 v[64:79], v[182:185], v[104:107], v[64:79]
	s_waitcnt lgkmcnt(0)
	v_mfma_f32_32x32x16_bf16 v[64:79], v[190:193], v[108:111], v[64:79]
	s_nop 11
	v_max3_f32 v182, v64, s9, v65
	v_max3_f32 v182, v182, v66, v67
	v_max3_f32 v182, v182, v68, v69
	v_max3_f32 v182, v182, v70, v71
	v_max3_f32 v182, v182, v72, v73
	v_max3_f32 v182, v182, v74, v75
	v_max3_f32 v182, v182, v76, v77
	v_max3_f32 v182, v182, v78, v79
	ds_bpermute_b32 v183, v161, v182
	s_waitcnt lgkmcnt(0)
	v_max3_f32 v196, v127, v182, v183
	v_sub_f32_e32 v127, v127, v196
	v_mul_f32_e32 v127, 0x3fb8aa3b, v127
	v_sub_f32_e32 v64, v64, v196
	v_sub_f32_e32 v65, v65, v196
	v_sub_f32_e32 v66, v66, v196
	v_sub_f32_e32 v67, v67, v196
	v_sub_f32_e32 v68, v68, v196
	v_sub_f32_e32 v69, v69, v196
	v_sub_f32_e32 v70, v70, v196
	v_sub_f32_e32 v71, v71, v196
	v_sub_f32_e32 v72, v72, v196
	v_sub_f32_e32 v73, v73, v196
	v_sub_f32_e32 v74, v74, v196
	v_sub_f32_e32 v75, v75, v196
	v_sub_f32_e32 v76, v76, v196
	v_sub_f32_e32 v77, v77, v196
	v_sub_f32_e32 v78, v78, v196
	v_sub_f32_e32 v79, v79, v196
	v_exp_f32_e32 v194, v127
	v_mul_f32_e32 v64, 0x3fb8aa3b, v64
	v_mul_f32_e32 v65, 0x3fb8aa3b, v65
	v_mul_f32_e32 v66, 0x3fb8aa3b, v66
	v_mul_f32_e32 v67, 0x3fb8aa3b, v67
	v_mul_f32_e32 v68, 0x3fb8aa3b, v68
	v_mul_f32_e32 v69, 0x3fb8aa3b, v69
	v_mul_f32_e32 v70, 0x3fb8aa3b, v70
	v_mul_f32_e32 v71, 0x3fb8aa3b, v71
	v_mul_f32_e32 v72, 0x3fb8aa3b, v72
	v_mul_f32_e32 v73, 0x3fb8aa3b, v73
	v_mul_f32_e32 v74, 0x3fb8aa3b, v74
	v_mul_f32_e32 v75, 0x3fb8aa3b, v75
	v_mul_f32_e32 v76, 0x3fb8aa3b, v76
	v_mul_f32_e32 v77, 0x3fb8aa3b, v77
	v_mul_f32_e32 v78, 0x3fb8aa3b, v78
	v_mul_f32_e32 v79, 0x3fb8aa3b, v79
	v_exp_f32_e32 v197, v64
	v_exp_f32_e32 v198, v65
	v_exp_f32_e32 v199, v66
	v_exp_f32_e32 v200, v67
	v_exp_f32_e32 v201, v68
	v_exp_f32_e32 v202, v69
	v_exp_f32_e32 v203, v70
	v_exp_f32_e32 v204, v71
	v_exp_f32_e32 v205, v72
	v_exp_f32_e32 v206, v73
	v_exp_f32_e32 v207, v74
	v_exp_f32_e32 v208, v75
	v_exp_f32_e32 v209, v76
	v_exp_f32_e32 v210, v77
	v_exp_f32_e32 v211, v78
	v_exp_f32_e32 v212, v79
	v_cvt_pk_bf16_f32 v64, v197, v198
	v_cvt_pk_bf16_f32 v65, v199, v200
	v_cvt_pk_bf16_f32 v66, v201, v202
	v_cvt_pk_bf16_f32 v67, v203, v204
	v_cvt_pk_bf16_f32 v68, v205, v206
	v_cvt_pk_bf16_f32 v69, v207, v208
	v_cvt_pk_bf16_f32 v70, v209, v210
	v_cvt_pk_bf16_f32 v71, v211, v212
	ds_read_b64 v[72:73], v129
	ds_read_b64 v[74:75], v133
	ds_read_b64 v[76:77], v135
	ds_read_b64 v[78:79], v137
	ds_read_b64 v[182:183], v139
	ds_read_b64 v[184:185], v141
	ds_read_b64 v[186:187], v143
	ds_read_b64 v[188:189], v145
	v_pk_mul_f32 v[62:63], v[62:63], v[194:195] op_sel_hi:[1,0]
	v_pk_mul_f32 v[60:61], v[60:61], v[194:195] op_sel_hi:[1,0]
	v_pk_mul_f32 v[58:59], v[58:59], v[194:195] op_sel_hi:[1,0]
	v_pk_mul_f32 v[56:57], v[56:57], v[194:195] op_sel_hi:[1,0]
	v_pk_mul_f32 v[54:55], v[54:55], v[194:195] op_sel_hi:[1,0]
	v_pk_mul_f32 v[52:53], v[52:53], v[194:195] op_sel_hi:[1,0]
	v_pk_mul_f32 v[50:51], v[50:51], v[194:195] op_sel_hi:[1,0]
	v_pk_mul_f32 v[48:49], v[48:49], v[194:195] op_sel_hi:[1,0]
	v_pk_mul_f32 v[46:47], v[46:47], v[194:195] op_sel_hi:[1,0]
	v_pk_mul_f32 v[44:45], v[44:45], v[194:195] op_sel_hi:[1,0]
	v_pk_mul_f32 v[42:43], v[42:43], v[194:195] op_sel_hi:[1,0]
	v_pk_mul_f32 v[40:41], v[40:41], v[194:195] op_sel_hi:[1,0]
	v_pk_mul_f32 v[38:39], v[38:39], v[194:195] op_sel_hi:[1,0]
	v_pk_mul_f32 v[36:37], v[36:37], v[194:195] op_sel_hi:[1,0]
	v_pk_mul_f32 v[34:35], v[34:35], v[194:195] op_sel_hi:[1,0]
	v_pk_mul_f32 v[32:33], v[32:33], v[194:195] op_sel_hi:[1,0]
	s_waitcnt lgkmcnt(6)
	v_mfma_f32_32x32x16_bf16 v[48:63], v[72:75], v[64:67], v[48:63]
	ds_read_b64 v[72:73], v147
	ds_read_b64 v[74:75], v149
	v_mul_f32_e64 v30, v30, v194
	v_mul_f32_e64 v31, v31, v194
	v_mul_f32_e64 v28, v28, v194
	v_mul_f32_e64 v29, v29, v194
	v_pk_mul_f32 v[26:27], v[26:27], v[194:195] op_sel_hi:[1,0]
	v_pk_mul_f32 v[24:25], v[24:25], v[194:195] op_sel_hi:[1,0]
	v_pk_mul_f32 v[22:23], v[22:23], v[194:195] op_sel_hi:[1,0]
	v_pk_mul_f32 v[20:21], v[20:21], v[194:195] op_sel_hi:[1,0]
	s_waitcnt lgkmcnt(4)
	v_mfma_f32_32x32x16_bf16 v[32:47], v[182:185], v[64:67], v[32:47]
	ds_read_b64 v[182:183], v151
	ds_read_b64 v[184:185], v153
	ds_read_b64 v[190:191], v155
	ds_read_b64 v[192:193], v181
	v_mul_f32_e64 v18, v18, v194
	v_mul_f32_e64 v19, v19, v194
	v_pk_mul_f32 v[16:17], v[16:17], v[194:195] op_sel_hi:[1,0]
	v_pk_mul_f32 v[14:15], v[14:15], v[194:195] op_sel_hi:[1,0]
	v_pk_mul_f32 v[12:13], v[12:13], v[194:195] op_sel_hi:[1,0]
	v_pk_mul_f32 v[10:11], v[10:11], v[194:195] op_sel_hi:[1,0]
	v_pk_mul_f32 v[8:9], v[8:9], v[194:195] op_sel_hi:[1,0]
	v_pk_mul_f32 v[6:7], v[6:7], v[194:195] op_sel_hi:[1,0]
	v_pk_mul_f32 v[4:5], v[4:5], v[194:195] op_sel_hi:[1,0]
	v_pk_mul_f32 v[2:3], v[2:3], v[194:195] op_sel_hi:[1,0]
	v_pk_mul_f32 v[0:1], v[0:1], v[194:195] op_sel_hi:[1,0]
	s_waitcnt lgkmcnt(4)
	v_mfma_f32_32x32x16_bf16 v[16:31], v[72:75], v[64:67], v[16:31]
	ds_read_b64 v[72:73], v195
	ds_read_b64 v[74:75], v131
	v_mov_b32_e32 v127, v196
	s_waitcnt lgkmcnt(2)
	v_mfma_f32_32x32x16_bf16 v[0:15], v[190:193], v[64:67], v[0:15]
	v_add_f32_e32 v65, 0, v197
	v_add_f32_e32 v65, v198, v65
	v_add_f32_e32 v65, v199, v65
	v_add_f32_e32 v65, v200, v65
	v_add_f32_e32 v65, v201, v65
	v_add_f32_e32 v65, v202, v65
	v_add_f32_e32 v65, v203, v65
	v_add_f32_e32 v65, v204, v65
	v_add_f32_e32 v65, v205, v65
	v_add_f32_e32 v65, v206, v65
	v_add_f32_e32 v65, v207, v65
	v_add_f32_e32 v65, v208, v65
	v_add_f32_e32 v65, v209, v65
	v_add_f32_e32 v65, v210, v65
	v_add_f32_e32 v65, v211, v65
	v_mfma_f32_32x32x16_bf16 v[48:63], v[76:79], v[68:71], v[48:63]
	v_add_f32_e32 v65, v212, v65
	ds_bpermute_b32 v66, v161, v65
	v_mov_b32_e32 v64, v125
	s_waitcnt lgkmcnt(0)
	v_add_f32_e32 v125, v65, v66
	v_mfma_f32_32x32x16_bf16 v[32:47], v[186:189], v[68:71], v[32:47]
	v_fmac_f32_e32 v125, v64, v194
	v_mfma_f32_32x32x16_bf16 v[16:31], v[182:185], v[68:71], v[16:31]
	v_mfma_f32_32x32x16_bf16 v[0:15], v[72:75], v[68:71], v[0:15]
	s_cbranch_scc1 .LBB0_1244
	v_div_scale_f32 v64, s[12:13], v125, v125, 1.0
	v_rcp_f32_e32 v65, v64
	v_div_scale_f32 v66, vcc, 1.0, v125, 1.0
	s_lshl_b32 s4, s4, 1
	v_fma_f32 v67, -v64, v65, 1.0
	v_fmac_f32_e32 v65, v67, v65
	v_mul_f32_e32 v67, v66, v65
	v_fma_f32 v68, -v64, v67, v66
	v_fmac_f32_e32 v67, v68, v65
	v_fma_f32 v64, -v64, v67, v66
	v_div_fmas_f32 v64, v64, v65, v67
	v_div_fixup_f32 v66, v64, v125, 1.0
	v_lshl_add_u64 v[64:65], s[2:3], 0, v[156:157]
	v_mul_f32_e32 v48, v48, v66
	v_mul_f32_e32 v49, v49, v66
	v_lshl_add_u64 v[64:65], v[64:65], 0, s[4:5]
	v_mov_b32_e32 v155, v113
	v_cvt_pk_bf16_f32 v48, v48, v49
	v_mul_f32_e32 v49, v50, v66
	v_lshl_add_u64 v[64:65], v[64:65], 0, v[154:155]
	v_mul_f32_e32 v50, v51, v66
	v_cvt_pk_bf16_f32 v49, v49, v50
	global_store_dwordx2 v[64:65], v[48:49], off sc0 sc1
	v_mul_f32_e32 v48, v52, v66
	v_mul_f32_e32 v49, v53, v66
	v_cvt_pk_bf16_f32 v48, v48, v49
	v_mul_f32_e32 v49, v54, v66
	v_mul_f32_e32 v50, v55, v66
	v_cvt_pk_bf16_f32 v49, v49, v50
	global_store_dwordx2 v[64:65], v[48:49], off offset:16 sc0 sc1
	v_mul_f32_e32 v48, v56, v66
	v_mul_f32_e32 v49, v57, v66
	v_cvt_pk_bf16_f32 v48, v48, v49
	v_mul_f32_e32 v49, v58, v66
	v_mul_f32_e32 v50, v59, v66
	v_cvt_pk_bf16_f32 v49, v49, v50
	global_store_dwordx2 v[64:65], v[48:49], off offset:32 sc0 sc1
	v_mul_f32_e32 v48, v60, v66
	v_mul_f32_e32 v49, v61, v66
	v_cvt_pk_bf16_f32 v48, v48, v49
	v_mul_f32_e32 v49, v62, v66
	v_mul_f32_e32 v32, v32, v66
	v_mul_f32_e32 v33, v33, v66
	v_mul_f32_e32 v50, v63, v66
	v_cvt_pk_bf16_f32 v49, v49, v50
	global_store_dwordx2 v[64:65], v[48:49], off offset:48 sc0 sc1
	v_cvt_pk_bf16_f32 v32, v32, v33
	v_mul_f32_e32 v33, v34, v66
	v_mul_f32_e32 v34, v35, v66
	v_cvt_pk_bf16_f32 v33, v33, v34
	global_store_dwordx2 v[64:65], v[32:33], off offset:64 sc0 sc1
	v_mul_f32_e32 v32, v36, v66
	v_mul_f32_e32 v33, v37, v66
	v_cvt_pk_bf16_f32 v32, v32, v33
	v_mul_f32_e32 v33, v38, v66
	v_mul_f32_e32 v34, v39, v66
	v_cvt_pk_bf16_f32 v33, v33, v34
	global_store_dwordx2 v[64:65], v[32:33], off offset:80 sc0 sc1
	v_mul_f32_e32 v32, v40, v66
	v_mul_f32_e32 v33, v41, v66
	v_cvt_pk_bf16_f32 v32, v32, v33
	v_mul_f32_e32 v33, v42, v66
	v_mul_f32_e32 v34, v43, v66
	v_cvt_pk_bf16_f32 v33, v33, v34
	global_store_dwordx2 v[64:65], v[32:33], off offset:96 sc0 sc1
	v_mul_f32_e32 v32, v44, v66
	v_mul_f32_e32 v33, v45, v66
	v_cvt_pk_bf16_f32 v32, v32, v33
	v_mul_f32_e32 v33, v46, v66
	v_mul_f32_e32 v16, v16, v66
	v_mul_f32_e32 v17, v17, v66
	v_mul_f32_e32 v34, v47, v66
	v_cvt_pk_bf16_f32 v33, v33, v34
	global_store_dwordx2 v[64:65], v[32:33], off offset:112 sc0 sc1
	v_cvt_pk_bf16_f32 v16, v16, v17
	v_mul_f32_e32 v17, v18, v66
	v_mul_f32_e32 v18, v19, v66
	v_cvt_pk_bf16_f32 v17, v17, v18
	global_store_dwordx2 v[64:65], v[16:17], off offset:128 sc0 sc1
	v_mul_f32_e32 v16, v20, v66
	v_mul_f32_e32 v17, v21, v66
	v_cvt_pk_bf16_f32 v16, v16, v17
	v_mul_f32_e32 v17, v22, v66
	v_mul_f32_e32 v18, v23, v66
	v_cvt_pk_bf16_f32 v17, v17, v18
	global_store_dwordx2 v[64:65], v[16:17], off offset:144 sc0 sc1
	v_mul_f32_e32 v16, v24, v66
	v_mul_f32_e32 v17, v25, v66
	v_cvt_pk_bf16_f32 v16, v16, v17
	v_mul_f32_e32 v17, v26, v66
	v_mul_f32_e32 v18, v27, v66
	v_cvt_pk_bf16_f32 v17, v17, v18
	global_store_dwordx2 v[64:65], v[16:17], off offset:160 sc0 sc1
	v_mul_f32_e32 v16, v28, v66
	v_mul_f32_e32 v17, v29, v66
	v_cvt_pk_bf16_f32 v16, v16, v17
	v_mul_f32_e32 v17, v30, v66
	v_mul_f32_e32 v0, v0, v66
	v_mul_f32_e32 v1, v1, v66
	v_mul_f32_e32 v18, v31, v66
	v_cvt_pk_bf16_f32 v17, v17, v18
	global_store_dwordx2 v[64:65], v[16:17], off offset:176 sc0 sc1
	v_cvt_pk_bf16_f32 v0, v0, v1
	v_mul_f32_e32 v1, v2, v66
	v_mul_f32_e32 v2, v3, v66
	v_cvt_pk_bf16_f32 v1, v1, v2
	global_store_dwordx2 v[64:65], v[0:1], off offset:192 sc0 sc1
	v_mul_f32_e32 v0, v4, v66
	v_mul_f32_e32 v1, v5, v66
	v_cvt_pk_bf16_f32 v0, v0, v1
	v_mul_f32_e32 v1, v6, v66
	v_mul_f32_e32 v2, v7, v66
	v_cvt_pk_bf16_f32 v1, v1, v2
	global_store_dwordx2 v[64:65], v[0:1], off offset:208 sc0 sc1
	v_mul_f32_e32 v0, v8, v66
	v_mul_f32_e32 v1, v9, v66
	v_cvt_pk_bf16_f32 v0, v0, v1
	v_mul_f32_e32 v1, v10, v66
	v_mul_f32_e32 v2, v11, v66
	v_cvt_pk_bf16_f32 v1, v1, v2
	global_store_dwordx2 v[64:65], v[0:1], off offset:224 sc0 sc1
	v_mul_f32_e32 v0, v12, v66
	v_mul_f32_e32 v1, v13, v66
	s_add_i32 s10, s10, s88
	v_cvt_pk_bf16_f32 v0, v0, v1
	v_mul_f32_e32 v1, v14, v66
	s_cmpk_lt_i32 s10, 0x80
	v_mul_f32_e32 v2, v15, v66
	v_cvt_pk_bf16_f32 v1, v1, v2
	global_store_dwordx2 v[64:65], v[0:1], off offset:240 sc0 sc1
	s_cbranch_scc1 .LBB0_1243

.Lmy_cv_wr:
	v_ashrrev_i32_e32 v5, 31, v4
	v_ashrrev_i32_e32 v7, 31, v6
	v_lshl_add_u64 v[4:5], v[4:5], 1, v[2:3]
	v_lshlrev_b64 v[122:123], 14, v[6:7]
	v_add_u32_e32 v110, 8, v6
	v_lshl_add_u64 v[122:123], v[4:5], 0, v[122:123]
	v_ashrrev_i32_e32 v111, 31, v110
	v_lshlrev_b64 v[110:111], 14, v[110:111]
	v_add_u32_e32 v112, 16, v6
	v_lshl_add_u64 v[110:111], v[4:5], 0, v[110:111]
	v_ashrrev_i32_e32 v113, 31, v112
	v_lshlrev_b64 v[112:113], 14, v[112:113]
	v_add_u32_e32 v114, 24, v6
	v_lshl_add_u64 v[112:113], v[4:5], 0, v[112:113]
	ds_write2_b32 v13, v46, v47 offset1:1
	ds_write2_b32 v13, v48, v49 offset0:2 offset1:3
	ds_write2_b32 v14, v50, v51 offset1:1
	ds_write2_b32 v15, v52, v53 offset1:1
	ds_write2_b32 v16, v54, v55 offset1:1
	ds_write2_b32 v17, v56, v57 offset1:1
	ds_write2_b32 v18, v58, v59 offset1:1
	ds_write2_b32 v19, v60, v61 offset1:1
	ds_write2_b32 v20, v62, v63 offset1:1
	ds_write2_b32 v21, v64, v65 offset1:1
	ds_write2_b32 v22, v66, v67 offset1:1
	ds_write2_b32 v23, v68, v69 offset1:1
	ds_write2_b32 v24, v70, v71 offset1:1
	ds_write2_b32 v25, v72, v73 offset1:1
	ds_write2_b32 v26, v74, v75 offset1:1
	ds_write2_b32 v27, v76, v77 offset1:1
	ds_write2_b32 v28, v78, v79 offset1:1
	ds_write2_b32 v29, v80, v81 offset1:1
	ds_write2_b32 v30, v82, v83 offset1:1
	ds_write2_b32 v31, v84, v85 offset1:1
	ds_write2_b32 v32, v86, v87 offset1:1
	ds_write2_b32 v33, v88, v89 offset1:1
	ds_write2_b32 v34, v90, v91 offset1:1
	ds_write2_b32 v35, v92, v93 offset1:1
	ds_write2_b32 v36, v94, v95 offset1:1
	ds_write2_b32 v37, v96, v97 offset1:1
	ds_write2_b32 v38, v98, v99 offset1:1
	ds_write2_b32 v39, v100, v101 offset1:1
	ds_write2_b32 v40, v102, v103 offset1:1
	ds_write2_b32 v41, v104, v105 offset1:1
	ds_write2_b32 v42, v106, v107 offset1:1
	ds_write2_b32 v43, v108, v109 offset1:1
	s_waitcnt lgkmcnt(0)
	ds_read2_b32 v[46:47], v11 offset1:65
	s_waitcnt lgkmcnt(0)
	v_cvt_pk_bf16_f32 v46, v46, v47
	ds_read2_b32 v[48:49], v11 offset0:130 offset1:195
	s_waitcnt lgkmcnt(0)
	v_cvt_pk_bf16_f32 v47, v48, v49
	ds_read2_b32 v[48:49], v44 offset0:4 offset1:69
	s_waitcnt lgkmcnt(0)
	v_cvt_pk_bf16_f32 v48, v48, v49
	ds_read2_b32 v[50:51], v44 offset0:134 offset1:199
	s_waitcnt lgkmcnt(0)
	v_cvt_pk_bf16_f32 v49, v50, v51
	ds_read2_b32 v[50:51], v11 offset0:8 offset1:73
	global_store_dwordx4 v[122:123], v[46:49], off sc0 sc1
	v_ashrrev_i32_e32 v115, 31, v114
	v_lshlrev_b64 v[114:115], 14, v[114:115]
	s_waitcnt lgkmcnt(0)
	v_cvt_pk_bf16_f32 v46, v50, v51
	ds_read2_b32 v[48:49], v11 offset0:138 offset1:203
	s_waitcnt lgkmcnt(0)
	v_cvt_pk_bf16_f32 v47, v48, v49
	ds_read2_b32 v[48:49], v44 offset0:12 offset1:77
	s_waitcnt lgkmcnt(0)
	v_cvt_pk_bf16_f32 v48, v48, v49
	ds_read2_b32 v[50:51], v44 offset0:142 offset1:207
	s_waitcnt lgkmcnt(0)
	v_cvt_pk_bf16_f32 v49, v50, v51
	ds_read2_b32 v[50:51], v11 offset0:16 offset1:81
	global_store_dwordx4 v[110:111], v[46:49], off sc0 sc1
	v_add_u32_e32 v116, 32, v6
	v_lshl_add_u64 v[114:115], v[4:5], 0, v[114:115]
	s_waitcnt lgkmcnt(0)
	v_cvt_pk_bf16_f32 v46, v50, v51
	ds_read2_b32 v[48:49], v11 offset0:146 offset1:211
	s_waitcnt lgkmcnt(0)
	v_cvt_pk_bf16_f32 v47, v48, v49
	ds_read2_b32 v[48:49], v44 offset0:20 offset1:85
	s_waitcnt lgkmcnt(0)
	v_cvt_pk_bf16_f32 v48, v48, v49
	ds_read2_b32 v[50:51], v44 offset0:150 offset1:215
	s_waitcnt lgkmcnt(0)
	v_cvt_pk_bf16_f32 v49, v50, v51
	ds_read2_b32 v[50:51], v11 offset0:24 offset1:89
	global_store_dwordx4 v[112:113], v[46:49], off sc0 sc1
	v_ashrrev_i32_e32 v117, 31, v116
	v_lshlrev_b64 v[116:117], 14, v[116:117]
	s_waitcnt lgkmcnt(0)
	v_cvt_pk_bf16_f32 v46, v50, v51
	ds_read2_b32 v[48:49], v11 offset0:154 offset1:219
	s_waitcnt lgkmcnt(0)
	v_cvt_pk_bf16_f32 v47, v48, v49
	ds_read2_b32 v[48:49], v44 offset0:28 offset1:93
	s_waitcnt lgkmcnt(0)
	v_cvt_pk_bf16_f32 v48, v48, v49
	ds_read2_b32 v[50:51], v44 offset0:158 offset1:223
	s_waitcnt lgkmcnt(0)
	v_cvt_pk_bf16_f32 v49, v50, v51
	ds_read2_b32 v[50:51], v11 offset0:32 offset1:97
	global_store_dwordx4 v[114:115], v[46:49], off sc0 sc1
	v_add_u32_e32 v118, 40, v6
	v_lshl_add_u64 v[116:117], v[4:5], 0, v[116:117]
	s_waitcnt lgkmcnt(0)
	v_cvt_pk_bf16_f32 v46, v50, v51
	ds_read2_b32 v[48:49], v11 offset0:162 offset1:227
	s_waitcnt lgkmcnt(0)
	v_cvt_pk_bf16_f32 v47, v48, v49
	ds_read2_b32 v[48:49], v44 offset0:36 offset1:101
	s_waitcnt lgkmcnt(0)
	v_cvt_pk_bf16_f32 v48, v48, v49
	ds_read2_b32 v[50:51], v44 offset0:166 offset1:231
	s_waitcnt lgkmcnt(0)
	v_cvt_pk_bf16_f32 v49, v50, v51
	v_ashrrev_i32_e32 v119, 31, v118
	ds_read2_b32 v[50:51], v11 offset0:40 offset1:105
	global_store_dwordx4 v[116:117], v[46:49], off sc0 sc1
	v_lshlrev_b64 v[118:119], 14, v[118:119]
	v_add_u32_e32 v120, 48, v6
	s_waitcnt lgkmcnt(0)
	v_cvt_pk_bf16_f32 v46, v50, v51
	ds_read2_b32 v[48:49], v11 offset0:170 offset1:235
	s_waitcnt lgkmcnt(0)
	v_cvt_pk_bf16_f32 v47, v48, v49
	ds_read2_b32 v[48:49], v44 offset0:44 offset1:109
	v_lshl_add_u64 v[118:119], v[4:5], 0, v[118:119]
	s_waitcnt lgkmcnt(0)
	v_cvt_pk_bf16_f32 v48, v48, v49
	ds_read2_b32 v[50:51], v44 offset0:174 offset1:239
	s_waitcnt lgkmcnt(0)
	v_cvt_pk_bf16_f32 v49, v50, v51
	v_ashrrev_i32_e32 v121, 31, v120
	ds_read2_b32 v[50:51], v11 offset0:48 offset1:113
	global_store_dwordx4 v[118:119], v[46:49], off sc0 sc1
	v_lshlrev_b64 v[120:121], 14, v[120:121]
	v_add_u32_e32 v6, 56, v6
	s_waitcnt lgkmcnt(0)
	v_cvt_pk_bf16_f32 v46, v50, v51
	ds_read2_b32 v[48:49], v11 offset0:178 offset1:243
	s_waitcnt lgkmcnt(0)
	v_cvt_pk_bf16_f32 v47, v48, v49
	ds_read2_b32 v[48:49], v44 offset0:52 offset1:117
	v_lshl_add_u64 v[120:121], v[4:5], 0, v[120:121]
	s_waitcnt lgkmcnt(0)
	v_cvt_pk_bf16_f32 v48, v48, v49
	ds_read2_b32 v[50:51], v44 offset0:182 offset1:247
	s_waitcnt lgkmcnt(0)
	v_cvt_pk_bf16_f32 v49, v50, v51
	v_ashrrev_i32_e32 v7, 31, v6
	ds_read2_b32 v[50:51], v11 offset0:56 offset1:121
	global_store_dwordx4 v[120:121], v[46:49], off sc0 sc1
	v_lshlrev_b64 v[6:7], 14, v[6:7]
	v_lshl_add_u64 v[4:5], v[4:5], 0, v[6:7]
	s_waitcnt lgkmcnt(0)
	v_cvt_pk_bf16_f32 v46, v50, v51
	ds_read2_b32 v[48:49], v11 offset0:186 offset1:251
	s_waitcnt lgkmcnt(0)
	v_cvt_pk_bf16_f32 v47, v48, v49
	ds_read2_b32 v[48:49], v44 offset0:60 offset1:125
	s_waitcnt lgkmcnt(0)
	v_cvt_pk_bf16_f32 v48, v48, v49
	ds_read2_b32 v[50:51], v44 offset0:190 offset1:255
	s_waitcnt lgkmcnt(0)
	v_cvt_pk_bf16_f32 v49, v50, v51
	global_store_dwordx4 v[4:5], v[46:49], off sc0 sc1
	s_waitcnt lgkmcnt(0)
	v_cmp_gt_i32_e32 vcc, s5, v132
	s_cbranch_vccz .LBB0_1257
	s_waitcnt vmcnt(8)
	v_mov_b32_e32 v46, v160
	v_mov_b32_e32 v47, v161
	v_mov_b32_e32 v48, v162
	v_mov_b32_e32 v49, v163
	v_mov_b32_e32 v50, v164
	v_mov_b32_e32 v51, v165
	v_mov_b32_e32 v52, v166
	v_mov_b32_e32 v53, v167
	v_mov_b32_e32 v54, v168
	v_mov_b32_e32 v55, v169
	v_mov_b32_e32 v56, v170
	v_mov_b32_e32 v57, v171
	v_mov_b32_e32 v58, v172
	v_mov_b32_e32 v59, v173
	v_mov_b32_e32 v60, v174
	v_mov_b32_e32 v61, v175
	v_mov_b32_e32 v62, v176
	v_mov_b32_e32 v63, v177
	v_mov_b32_e32 v64, v178
	v_mov_b32_e32 v65, v179
	v_mov_b32_e32 v66, v180
	v_mov_b32_e32 v67, v181
	v_mov_b32_e32 v68, v182
	v_mov_b32_e32 v69, v183
	v_mov_b32_e32 v70, v184
	v_mov_b32_e32 v71, v185
	v_mov_b32_e32 v72, v186
	v_mov_b32_e32 v73, v187
	v_mov_b32_e32 v74, v188
	v_mov_b32_e32 v75, v189
	v_mov_b32_e32 v76, v190
	v_mov_b32_e32 v77, v191
	v_mov_b32_e32 v78, v192
	v_mov_b32_e32 v79, v193
	v_mov_b32_e32 v80, v194
	v_mov_b32_e32 v81, v195
	v_mov_b32_e32 v82, v196
	v_mov_b32_e32 v83, v197
	v_mov_b32_e32 v84, v198
	v_mov_b32_e32 v85, v199
	v_mov_b32_e32 v86, v200
	v_mov_b32_e32 v87, v201
	v_mov_b32_e32 v88, v202
	v_mov_b32_e32 v89, v203
	v_mov_b32_e32 v90, v204
	v_mov_b32_e32 v91, v205
	v_mov_b32_e32 v92, v206
	v_mov_b32_e32 v93, v207
	v_mov_b32_e32 v94, v208
	v_mov_b32_e32 v95, v209
	v_mov_b32_e32 v96, v210
	v_mov_b32_e32 v97, v211
	v_mov_b32_e32 v98, v212
	v_mov_b32_e32 v99, v213
	v_mov_b32_e32 v100, v214
	v_mov_b32_e32 v101, v215
	v_mov_b32_e32 v102, v216
	v_mov_b32_e32 v103, v217
	v_mov_b32_e32 v104, v218
	v_mov_b32_e32 v105, v219
	v_mov_b32_e32 v106, v220
	v_mov_b32_e32 v107, v221
	v_mov_b32_e32 v108, v222
	v_mov_b32_e32 v109, v223
	v_mov_b32_e32 v4, v246
	v_mov_b32_e32 v6, v248
	v_mov_b32_e32 v8, v132
	v_mov_b32_e32 v12, v133
	s_branch .Lmy_cv_loop
